# FFT stage-2 units: loads hoisted + 6-unit software-pipelined burst with the DFT table staged in LDS
# speedup vs baseline: 1.1676x; 1.0073x over previous
.LBB0_233:
	s_or_b64 exec, exec, s[0:1]
	s_cmpk_gt_i32 s10, 0x17ff
	v_lshlrev_b32_e32 v196, 3, v197
	v_lshlrev_b32_e32 v194, 4, v190
	s_waitcnt lgkmcnt(0)
	s_barrier
	s_cbranch_scc1 .LBB0_244
	s_mov_b32 s98, 0
	s_cmpk_lg_i32 s68, 0x100
	s_cbranch_scc1 .Lp2_entry
	s_mov_b32 s86, s11
	s_mov_b32 s87, s64
	s_mov_b32 s88, s76
	s_mov_b32 s89, s77
	s_mov_b64 s[90:91], s[20:21]
	s_mov_b64 s[92:93], s[22:23]
	s_mov_b64 s[94:95], s[26:27]
	s_mov_b32 s45, s75
	s_mul_i32 s46, s45, 0x4001
	s_lshr_b32 s46, s46, 16
	s_mul_i32 s46, s46, 4
	s_sub_u32 s45, s45, s46
	s_mov_b32 s44, 0
	s_mov_b32 s98, 2
	s_cmp_eq_u32 s45, 0
	s_cbranch_scc1 .Lp2_entry
	s_mov_b32 s98, 1
	s_branch .Lp3_enter

.Lp3_pre:
	global_load_dword v1, v0, s[20:21]
	global_load_dword v2, v0, s[22:23]
	v_mbcnt_hi_u32_b32 v0, -1, v218
	v_and_b32_e32 v3, 64, v0
	v_xor_b32_e32 v4, 1, v0
	v_add_u32_e32 v3, 64, v3
	v_cmp_lt_i32_e32 vcc, v4, v3
	v_xor_b32_e32 v5, 2, v0
	v_xor_b32_e32 v6, 4, v0
	v_cndmask_b32_e32 v4, v0, v4, vcc
	v_lshlrev_b32_e32 v142, 2, v4
	v_cmp_lt_i32_e32 vcc, v5, v3
	v_xor_b32_e32 v7, 8, v0
	v_xor_b32_e32 v8, 16, v0
	v_cndmask_b32_e32 v5, v0, v5, vcc
	v_lshlrev_b32_e32 v143, 2, v5
	v_cmp_lt_i32_e32 vcc, v6, v3
	v_xor_b32_e32 v9, 32, v0
	s_add_u32 s0, s42, 0x11800000
	v_cndmask_b32_e32 v6, v0, v6, vcc
	v_lshlrev_b32_e32 v144, 2, v6
	v_cmp_lt_i32_e32 vcc, v7, v3
	s_addc_u32 s1, s43, 0
	v_mov_b32_e32 v99, 0
	v_cndmask_b32_e32 v6, v0, v7, vcc
	v_lshlrev_b32_e32 v145, 2, v6
	v_cmp_lt_i32_e32 vcc, v8, v3
	s_mov_b32 s17, 0
	s_cmpk_lt_i32 s75, 0xc00
	v_cndmask_b32_e32 v6, v0, v8, vcc
	v_lshlrev_b32_e32 v146, 2, v6
	v_cmp_lt_i32_e32 vcc, v9, v3
	s_waitcnt vmcnt(1)
	v_and_b32_e32 v4, 0x7fffffff, v1
	s_waitcnt vmcnt(0)
	v_and_b32_e32 v10, 0x7fffffff, v2
	ds_bpermute_b32 v4, v142, v4
	ds_bpermute_b32 v10, v142, v10
	v_max_f32_e64 v1, |v1|, |v1|
	v_max_f32_e64 v2, |v2|, |v2|
	v_cndmask_b32_e32 v0, v0, v9, vcc
	s_waitcnt lgkmcnt(1)
	v_max_f32_e32 v4, v4, v4
	s_waitcnt lgkmcnt(0)
	v_max_f32_e32 v5, v10, v10
	v_max_f32_e32 v1, v1, v4
	v_max_f32_e32 v2, v2, v5
	ds_bpermute_b32 v4, v143, v1
	ds_bpermute_b32 v5, v143, v2
	v_lshlrev_b32_e32 v147, 2, v0
	s_waitcnt lgkmcnt(1)
	v_max_f32_e32 v4, v4, v4
	s_waitcnt lgkmcnt(0)
	v_max_f32_e32 v5, v5, v5
	v_max_f32_e32 v1, v1, v4
	v_max_f32_e32 v2, v2, v5
	ds_bpermute_b32 v4, v144, v1
	ds_bpermute_b32 v5, v144, v2
	s_waitcnt lgkmcnt(1)
	v_max_f32_e32 v4, v4, v4
	s_waitcnt lgkmcnt(0)
	v_max_f32_e32 v5, v5, v5
	v_max_f32_e32 v1, v1, v4
	v_max_f32_e32 v2, v2, v5
	ds_bpermute_b32 v4, v145, v1
	ds_bpermute_b32 v5, v145, v2
	s_waitcnt lgkmcnt(1)
	v_max_f32_e32 v4, v4, v4
	s_waitcnt lgkmcnt(0)
	v_max_f32_e32 v5, v5, v5
	v_max_f32_e32 v1, v1, v4
	v_max_f32_e32 v2, v2, v5
	ds_bpermute_b32 v4, v146, v1
	ds_bpermute_b32 v5, v146, v2
	s_waitcnt lgkmcnt(1)
	v_max_f32_e32 v0, v4, v4
	s_waitcnt lgkmcnt(0)
	v_max_f32_e32 v3, v5, v5
	v_max_f32_e32 v0, v1, v0
	v_max_f32_e32 v1, v2, v3
	ds_bpermute_b32 v2, v147, v0
	ds_bpermute_b32 v3, v147, v1
	s_waitcnt lgkmcnt(1)
	v_max_f32_e32 v2, v2, v2
	s_waitcnt lgkmcnt(0)
	v_max_f32_e32 v3, v3, v3
	v_max_f32_e32 v0, v0, v2
	v_max_f32_e32 v1, v1, v3
	v_mul_f32_e32 v0, 0x4138aa3b, v0
	v_mul_f32_e32 v0, v0, v1
	s_nop 0
	v_readfirstlane_b32 s2, v0
	s_cbranch_scc0 .LBB0_320
	v_mov_b32_e32 v0, 0x42200000
	s_lshl_b32 s4, s74, 12
	v_lshrrev_b32_e32 v148, 3, v191
	v_cmp_nlt_f32_e64 s[2:3], s2, v0
	s_lshl_b32 s18, s74, 5
	s_add_i32 s4, s4, 0
	s_mov_b32 s19, s17
	v_xor_b32_e32 v0, v148, v191
	s_add_i32 s11, s4, 0x10000
	s_lshl_b64 s[4:5], s[18:19], 2
	v_lshlrev_b32_e32 v0, 4, v0
	s_add_u32 s4, s26, s4
	v_and_b32_e32 v0, 48, v0
	v_lshlrev_b32_e32 v2, 7, v148
	v_xor_b32_e32 v3, v212, v191
	s_movk_i32 s6, 0x70
	s_addc_u32 s5, s27, s5
	v_lshlrev_b32_e32 v98, 4, v197
	v_add_u32_e32 v4, s11, v0
	v_and_b32_e32 v0, 4, v191
	v_and_or_b32 v2, v3, s6, v2
	v_bfe_u32 v3, v191, 1, 3
	v_bitop3_b32 v14, v197, v219, 7 bitop3:0x78
	v_lshl_add_u64 v[100:101], s[4:5], 0, v[98:99]
	v_cmp_eq_u32_e64 s[4:5], 0, v0
	v_and_b32_e32 v0, 56, v220
	v_readlane_b32 s8, v254, 22
	v_lshlrev_b32_e32 v156, 4, v14
	v_bitop3_b32 v14, v197, v3, 2 bitop3:0x36
	v_add_u32_e32 v150, 0, v2
	v_lshlrev_b32_e32 v2, 7, v189
	v_lshlrev_b32_e32 v98, 1, v0
	v_readlane_b32 s9, v254, 23
	v_lshlrev_b32_e32 v157, 4, v14
	v_bitop3_b32 v14, v197, v3, 4 bitop3:0x36
	v_bitop3_b32 v3, v197, v3, 6 bitop3:0x36
	v_add_u32_e32 v151, 0, v2
	v_add_u32_e32 v5, s11, v2
	v_and_b32_e32 v2, 15, v191
	v_lshl_add_u64 v[102:103], s[8:9], 0, v[98:99]
	v_readlane_b32 s8, v254, 5
	v_lshlrev_b32_e32 v159, 4, v3
	v_bitop3_b32 v3, v197, v191, 15 bitop3:0x78
	v_mov_b32_e32 v195, v99
	v_readlane_b32 s9, v254, 6
	v_lshlrev_b32_e32 v158, 4, v14
	v_lshlrev_b32_e32 v14, 3, v3
	v_bitop3_b32 v3, v197, v2, 2 bitop3:0x36
	v_lshl_add_u64 v[106:107], s[8:9], 0, v[194:195]
	s_mov_b64 s[8:9], 0x1000
	v_lshlrev_b32_e32 v15, 3, v3
	v_bitop3_b32 v3, v197, v2, 4 bitop3:0x36
	v_lshl_add_u64 v[108:109], v[106:107], 0, s[8:9]
	s_mov_b64 s[8:9], 0x1400
	v_lshlrev_b32_e32 v16, 3, v3
	v_bitop3_b32 v3, v197, v2, 6 bitop3:0x36
	v_lshl_add_u64 v[110:111], v[106:107], 0, s[8:9]
	s_mov_b64 s[8:9], 0x1800
	v_lshlrev_b32_e32 v17, 3, v3
	v_bitop3_b32 v3, v197, v2, 8 bitop3:0x36
	v_lshl_add_u64 v[112:113], v[106:107], 0, s[8:9]
	s_mov_b64 s[8:9], 0x1c00
	v_lshlrev_b32_e32 v18, 3, v3
	v_bitop3_b32 v3, v197, v2, 10 bitop3:0x36
	v_lshrrev_b32_e32 v152, 3, v190
	v_lshl_add_u64 v[114:115], v[106:107], 0, s[8:9]
	s_mov_b64 s[8:9], 0x2000
	v_lshlrev_b32_e32 v19, 3, v3
	v_bitop3_b32 v3, v197, v2, 12 bitop3:0x36
	v_bitop3_b32 v2, v197, v2, 14 bitop3:0x36
	v_lshl_add_u64 v[116:117], v[106:107], 0, s[8:9]
	s_mov_b64 s[8:9], 0x2400
	v_lshlrev_b32_e32 v21, 3, v2
	v_and_b32_e32 v2, 0x70, v212
	v_or_b32_e32 v160, 8, v152
	v_lshl_add_u64 v[118:119], v[106:107], 0, s[8:9]
	s_mov_b64 s[8:9], 0x2800
	v_bitop3_b32 v23, v191, v2, 48 bitop3:0x6c
	v_lshrrev_b32_e32 v2, 1, v160
	v_lshl_add_u64 v[120:121], v[106:107], 0, s[8:9]
	s_mov_b64 s[8:9], 0x2c00
	v_xor_b32_e32 v2, v2, v191
	v_lshl_add_u64 v[122:123], v[106:107], 0, s[8:9]
	s_mov_b64 s[8:9], 0x3000
	v_lshlrev_b32_e32 v2, 4, v2
	v_or_b32_e32 v162, 24, v152
	v_lshl_add_u64 v[124:125], v[106:107], 0, s[8:9]
	s_mov_b64 s[8:9], 0x3400
	v_and_b32_e32 v25, 0x70, v2
	v_lshrrev_b32_e32 v2, 1, v162
	v_lshl_add_u64 v[126:127], v[106:107], 0, s[8:9]
	s_mov_b64 s[8:9], 0x3800
	v_xor_b32_e32 v2, v2, v191
	v_and_b32_e32 v6, 8, v191
	v_lshl_add_u64 v[104:105], s[0:1], 0, v[98:99]
	v_lshl_add_u64 v[128:129], v[106:107], 0, s[8:9]
	s_mov_b64 s[8:9], 0x3c00
	v_lshlrev_b32_e32 v2, 4, v2
	v_lshlrev_b32_e32 v98, 4, v217
	v_cmp_eq_u32_e64 s[6:7], 0, v6
	v_lshl_add_u64 v[130:131], v[106:107], 0, s[8:9]
	v_bitop3_b32 v6, v197, v191, 7 bitop3:0x78
	v_bitop3_b32 v7, v197, v217, 2 bitop3:0x36
	v_bitop3_b32 v8, v197, v217, 4 bitop3:0x36
	v_bitop3_b32 v9, v197, v217, 6 bitop3:0x36
	v_or_b32_e32 v153, 16, v193
	v_or_b32_e32 v154, 32, v193
	v_or_b32_e32 v155, 48, v193
	v_lshlrev_b32_e32 v20, 3, v3
	v_or_b32_e32 v161, 16, v152
	v_and_b32_e32 v28, 0x70, v2
	v_lshl_add_u64 v[2:3], s[42:43], 0, v[98:99]
	s_mov_b64 s[8:9], 0xac00100
	v_lshl_add_u32 v1, v189, 6, s11
	v_lshlrev_b32_e32 v6, 3, v6
	v_lshlrev_b32_e32 v7, 3, v7
	v_lshlrev_b32_e32 v8, 3, v8
	v_lshlrev_b32_e32 v9, 3, v9
	v_lshlrev_b32_e32 v10, 6, v193
	v_lshlrev_b32_e32 v11, 6, v153
	v_lshlrev_b32_e32 v12, 6, v154
	v_lshlrev_b32_e32 v13, 6, v155
	v_lshl_add_u32 v22, v152, 7, s11
	v_lshl_add_u32 v24, v160, 7, s11
	v_lshl_add_u32 v26, v161, 7, s11
	v_lshl_add_u32 v27, v162, 7, s11
	v_lshl_add_u64 v[132:133], v[2:3], 0, s[8:9]
	s_mov_b64 s[8:9], 0xa008000
	v_and_b32_e32 v149, 24, v220
	v_lshl_add_u64 v[134:135], v[2:3], 0, s[8:9]
	v_add_u32_e32 v163, v1, v6
	v_add_u32_e32 v164, v1, v7
	v_add_u32_e32 v165, v1, v8
	v_add_u32_e32 v166, v1, v9
	v_add_u32_e32 v167, v4, v10
	v_add_u32_e32 v168, v4, v11
	v_add_u32_e32 v169, v4, v12
	v_add_u32_e32 v170, v4, v13
	v_lshlrev_b32_e32 v136, 1, v0
	s_movk_i32 s11, 0x4000
	s_mov_b32 s19, 0x41000000
	s_mov_b64 s[20:21], 0x80
	v_add_u32_e32 v171, v5, v14
	v_add_u32_e32 v172, v5, v15
	v_add_u32_e32 v173, v5, v16
	v_add_u32_e32 v174, v5, v17
	v_add_u32_e32 v175, v5, v18
	v_add_u32_e32 v176, v5, v19
	v_add_u32_e32 v177, v5, v20
	v_add_u32_e32 v178, v5, v21
	v_add_u32_e32 v179, v22, v23
	v_add_u32_e32 v180, v24, v25
	v_add_u32_e32 v181, v26, v23
	v_add_u32_e32 v182, v27, v28
	v_mov_b32_e32 v183, 0x3c3504f3
	v_mov_b32_e32 v184, 0x3c800000
	s_mov_b32 s28, s75
	s_cmp_eq_u32 s98, 0
	s_cbranch_scc1 .LBB0_300
	s_cmp_eq_u32 s98, 2
	s_cbranch_scc1 .Lp23_resume
	s_mov_b32 s44, -1
	s_cmp_eq_u32 s98, 1
	s_cbranch_scc0 .Lp23_clsB
	s_mov_b32 s45, s75
	s_mul_i32 s46, s45, 0x4001
	s_lshr_b32 s46, s46, 16
	s_mul_i32 s46, s46, 4
	s_sub_u32 s45, s45, s46
	s_branch .LBB0_299
.Lp23_clsB:
	s_lshr_b32 s45, s75, 2
	s_mul_i32 s46, s45, 0x4001
	s_lshr_b32 s46, s46, 16
	s_mul_i32 s46, s46, 4
	s_sub_u32 s45, s45, s46
	s_branch .LBB0_299

.Lp23_B:
	s_cmp_gt_u32 s44, 8
	s_cbranch_scc1 .LBB0_320
	s_add_i32 s28, s44, 3
	s_cmp_lt_u32 s44, s45
	s_cbranch_scc1 .Lp23_set
	s_cmp_eq_u32 s44, s45
	s_cbranch_scc1 .Lfb_entry
	s_add_i32 s28, s44, 6
	s_sub_u32 s28, s28, s45
	s_cmp_lt_u32 s28, 12
	s_cbranch_scc1 .Lp23_set
	s_add_i32 s28, s44, -3
	s_branch .Lp23_set

.LBB0_306:
	s_lshr_b32 s9, s28, 1
	s_and_b32 s16, s9, s8
	s_lshl_b32 s8, s22, 13
	s_add_i32 s25, s8, 0xffff8000
	s_lshl_b32 s8, s28, 8
	s_and_b32 s23, s8, 0x100
	s_lshl_b32 s26, s22, 12
	s_add_i32 s24, s23, s18
	s_cmp_lt_u32 s22, 8
	s_cselect_b64 vcc, -1, 0
	s_and_b64 s[8:9], vcc, exec
	s_cselect_b32 s8, s26, s25
	v_or_b32_e32 v98, s24, v189
	s_cselect_b32 s22, 6, 7
	s_ashr_i32 s9, s8, 31
	s_lshl_b64 s[26:27], s[8:9], 11
	v_lshlrev_b64 v[96:97], s22, v[98:99]
	s_add_u32 s26, s42, s26
	v_lshl_add_u64 v[96:97], v[96:97], 0, s[16:17]
	s_addc_u32 s27, s43, s27
	v_lshlrev_b64 v[96:97], 8, v[96:97]
	v_lshl_add_u64 v[96:97], s[26:27], 0, v[96:97]
	v_lshlrev_b32_e32 v98, 1, v196
	v_lshl_add_u64 v[96:97], v[96:97], 0, v[98:99]
	global_load_dwordx4 v[0:3], v[96:97], off
	global_load_dwordx4 v[4:7], v[96:97], off offset:32
	global_load_dwordx4 v[8:11], v[96:97], off offset:64
	global_load_dwordx4 v[12:15], v[96:97], off offset:96
	global_load_dwordx4 v[16:19], v[96:97], off offset:128
	global_load_dwordx4 v[20:23], v[96:97], off offset:160
	global_load_dwordx4 v[24:27], v[96:97], off offset:192
	global_load_dwordx4 v[28:31], v[96:97], off offset:224
	global_load_dwordx4 v[32:35], v[106:107], off
	global_load_dwordx4 v[36:39], v[106:107], off offset:1024
	global_load_dwordx4 v[40:43], v[106:107], off offset:2048
	global_load_dwordx4 v[44:47], v[106:107], off offset:3072
	global_load_dwordx4 v[48:51], v[108:109], off
	global_load_dwordx4 v[52:55], v[110:111], off
	global_load_dwordx4 v[56:59], v[112:113], off
	global_load_dwordx4 v[60:63], v[114:115], off
	s_or_b32 s8, s8, s16
	v_or_b32_e32 v185, s24, v149
	v_lshlrev_b32_e32 v98, 1, v185
	s_mov_b32 s25, s17
	s_lshl_b32 s24, s23, 2
	v_lshl_add_u64 v[186:187], v[100:101], 0, s[24:25]
	v_cndmask_b32_e32 v195, v183, v184, vcc
	v_lshl_add_u64 v[198:199], s[76:77], 0, v[98:99]
	global_load_dwordx4 v[80:83], v[186:187], off
	global_load_dwordx4 v[84:87], v[186:187], off offset:32
	global_load_dwordx4 v[88:91], v[186:187], off offset:64
	global_load_dwordx4 v[92:95], v[186:187], off offset:96
	v_lshlrev_b32_e32 v137, s22, v193
	v_add_u32_e32 v137, s8, v137
	v_ashrrev_i32_e32 v201, 31, v137
	v_mov_b32_e32 v200, v137
	v_lshlrev_b64 v[200:201], 10, v[200:201]
	v_lshl_add_u64 v[200:201], v[198:199], 0, v[200:201]
	global_load_dwordx4 v[64:67], v[200:201], off
	v_lshlrev_b32_e32 v138, s22, v153
	v_add_u32_e32 v138, s8, v138
	v_ashrrev_i32_e32 v201, 31, v138
	v_mov_b32_e32 v200, v138
	v_lshlrev_b64 v[200:201], 10, v[200:201]
	v_lshl_add_u64 v[200:201], v[198:199], 0, v[200:201]
	global_load_dwordx4 v[68:71], v[200:201], off
	v_lshlrev_b32_e32 v139, s22, v154
	v_add_u32_e32 v139, s8, v139
	v_ashrrev_i32_e32 v201, 31, v139
	v_mov_b32_e32 v200, v139
	v_lshlrev_b64 v[200:201], 10, v[200:201]
	v_lshl_add_u64 v[200:201], v[198:199], 0, v[200:201]
	global_load_dwordx4 v[72:75], v[200:201], off
	v_lshlrev_b32_e32 v140, s22, v155
	v_add_u32_e32 v140, s8, v140
	v_ashrrev_i32_e32 v201, 31, v140
	v_mov_b32_e32 v200, v140
	v_lshlrev_b64 v[200:201], 10, v[200:201]
	v_lshl_add_u64 v[200:201], v[198:199], 0, v[200:201]
	global_load_dwordx4 v[76:79], v[200:201], off
	s_waitcnt vmcnt(23)
	s_waitcnt vmcnt(15)
	v_mfma_f32_32x32x16_bf16 v[222:237], v[0:3], v[32:35], 0
	s_waitcnt vmcnt(14)
	v_mfma_f32_32x32x16_bf16 v[238:253], v[0:3], v[36:39], 0
	global_load_dwordx4 v[32:35], v[116:117], off
	global_load_dwordx4 v[36:39], v[118:119], off
	s_waitcnt vmcnt(15)
	v_mfma_f32_32x32x16_bf16 v[222:237], v[4:7], v[40:43], v[222:237]
	s_waitcnt vmcnt(14)
	v_mfma_f32_32x32x16_bf16 v[238:253], v[4:7], v[44:47], v[238:253]
	global_load_dwordx4 v[40:43], v[120:121], off
	global_load_dwordx4 v[44:47], v[122:123], off
	s_waitcnt vmcnt(15)
	v_mfma_f32_32x32x16_bf16 v[222:237], v[8:11], v[48:51], v[222:237]
	s_waitcnt vmcnt(14)
	v_mfma_f32_32x32x16_bf16 v[238:253], v[8:11], v[52:55], v[238:253]
	global_load_dwordx4 v[48:51], v[124:125], off
	global_load_dwordx4 v[52:55], v[126:127], off
	s_waitcnt vmcnt(15)
	v_mfma_f32_32x32x16_bf16 v[222:237], v[12:15], v[56:59], v[222:237]
	s_waitcnt vmcnt(14)
	v_mfma_f32_32x32x16_bf16 v[238:253], v[12:15], v[60:63], v[238:253]
	global_load_dwordx4 v[56:59], v[128:129], off
	global_load_dwordx4 v[60:63], v[130:131], off
	s_waitcnt vmcnt(7)
	v_mfma_f32_32x32x16_bf16 v[222:237], v[16:19], v[32:35], v[222:237]
	s_waitcnt vmcnt(6)
	v_mfma_f32_32x32x16_bf16 v[238:253], v[16:19], v[36:39], v[238:253]
	s_waitcnt vmcnt(5)
	v_mfma_f32_32x32x16_bf16 v[222:237], v[20:23], v[40:43], v[222:237]
	s_waitcnt vmcnt(4)
	v_mfma_f32_32x32x16_bf16 v[238:253], v[20:23], v[44:47], v[238:253]
	s_waitcnt vmcnt(3)
	v_mfma_f32_32x32x16_bf16 v[222:237], v[24:27], v[48:51], v[222:237]
	s_waitcnt vmcnt(2)
	v_mfma_f32_32x32x16_bf16 v[238:253], v[24:27], v[52:55], v[238:253]
	s_waitcnt vmcnt(1)
	v_mfma_f32_32x32x16_bf16 v[222:237], v[28:31], v[56:59], v[222:237]
	s_waitcnt vmcnt(0)
	v_mfma_f32_32x32x16_bf16 v[238:253], v[28:31], v[60:63], v[238:253]
	s_nop 7
	s_nop 7
	v_fma_f32 v222, v195, v222, v80
	v_fma_f32 v223, v195, v223, v81
	v_fma_f32 v224, v195, v224, v82
	v_fma_f32 v225, v195, v225, v83
	v_fma_f32 v226, v195, v226, v84
	v_fma_f32 v227, v195, v227, v85
	v_fma_f32 v228, v195, v228, v86
	v_fma_f32 v229, v195, v229, v87
	v_fma_f32 v230, v195, v230, v88
	v_fma_f32 v231, v195, v231, v89
	v_fma_f32 v232, v195, v232, v90
	v_fma_f32 v233, v195, v233, v91
	v_fma_f32 v234, v195, v234, v92
	v_fma_f32 v235, v195, v235, v93
	v_fma_f32 v236, v195, v236, v94
	v_fma_f32 v237, v195, v237, v95
	v_fma_f32 v238, v195, v238, v80
	v_fma_f32 v239, v195, v239, v81
	v_fma_f32 v240, v195, v240, v82
	v_fma_f32 v241, v195, v241, v83
	v_fma_f32 v242, v195, v242, v84
	v_fma_f32 v243, v195, v243, v85
	v_fma_f32 v244, v195, v244, v86
	v_fma_f32 v245, v195, v245, v87
	v_fma_f32 v246, v195, v246, v88
	v_fma_f32 v247, v195, v247, v89
	v_fma_f32 v248, v195, v248, v90
	v_fma_f32 v249, v195, v249, v91
	v_fma_f32 v250, v195, v250, v92
	v_fma_f32 v251, v195, v251, v93
	v_fma_f32 v252, v195, v252, v94
	v_fma_f32 v253, v195, v253, v95
	v_cvt_pk_bf16_f32 v0, v222, v223
	v_cvt_pk_bf16_f32 v1, v224, v225
	v_cvt_pk_bf16_f32 v2, v226, v227
	v_cvt_pk_bf16_f32 v3, v228, v229
	v_cvt_pk_bf16_f32 v4, v230, v231
	v_cvt_pk_bf16_f32 v5, v232, v233
	v_cvt_pk_bf16_f32 v6, v234, v235
	v_cvt_pk_bf16_f32 v7, v236, v237
	v_cvt_pk_bf16_f32 v8, v238, v239
	v_cvt_pk_bf16_f32 v9, v240, v241
	v_cvt_pk_bf16_f32 v10, v242, v243
	v_cvt_pk_bf16_f32 v11, v244, v245
	v_cvt_pk_bf16_f32 v12, v246, v247
	v_cvt_pk_bf16_f32 v13, v248, v249
	v_cvt_pk_bf16_f32 v14, v250, v251
	v_cvt_pk_bf16_f32 v15, v252, v253
	ds_write2st64_b64 v163, v[0:1], v[8:9] offset1:4
	ds_write2st64_b64 v164, v[2:3], v[10:11] offset1:4
	ds_write2st64_b64 v165, v[4:5], v[12:13] offset1:4
	ds_write2st64_b64 v166, v[6:7], v[14:15] offset1:4
	ds_read_b128 v[16:19], v167
	ds_read_b128 v[20:23], v168
	ds_read_b128 v[24:27], v169
	ds_read_b128 v[28:31], v170
	s_waitcnt lgkmcnt(3)
	v_cndmask_b32_e64 v35, v17, v19, s[4:5]
	v_cndmask_b32_e64 v34, v16, v18, s[4:5]
	v_cndmask_b32_e64 v33, v19, v17, s[4:5]
	v_cndmask_b32_e64 v32, v18, v16, s[4:5]
	v_lshlrev_b32_e32 v40, 16, v32
	v_and_b32_e32 v41, 0xffff0000, v32
	v_lshlrev_b32_e32 v42, 16, v64
	v_and_b32_e32 v43, 0xffff0000, v64
	v_pk_mul_f32 v[40:41], v[42:43], v[40:41]
	v_cvt_pk_bf16_f32 v44, v40, v41
	v_lshlrev_b32_e32 v40, 16, v33
	v_and_b32_e32 v41, 0xffff0000, v33
	v_lshlrev_b32_e32 v42, 16, v65
	v_and_b32_e32 v43, 0xffff0000, v65
	v_pk_mul_f32 v[40:41], v[42:43], v[40:41]
	v_cvt_pk_bf16_f32 v45, v40, v41
	v_lshlrev_b32_e32 v40, 16, v34
	v_and_b32_e32 v41, 0xffff0000, v34
	v_lshlrev_b32_e32 v42, 16, v66
	v_and_b32_e32 v43, 0xffff0000, v66
	v_pk_mul_f32 v[40:41], v[42:43], v[40:41]
	v_cvt_pk_bf16_f32 v46, v40, v41
	v_lshlrev_b32_e32 v40, 16, v35
	v_and_b32_e32 v41, 0xffff0000, v35
	v_lshlrev_b32_e32 v42, 16, v67
	v_and_b32_e32 v43, 0xffff0000, v67
	v_pk_mul_f32 v[40:41], v[42:43], v[40:41]
	v_cvt_pk_bf16_f32 v47, v40, v41
	v_ashrrev_i32_e32 v201, 31, v137
	v_mov_b32_e32 v200, v137
	v_lshlrev_b64 v[200:201], 11, v[200:201]
	v_lshl_add_u64 v[200:201], s[0:1], 0, v[200:201]
	v_lshl_add_u64 v[200:201], v[200:201], 0, v[98:99]
	global_store_dwordx4 v[200:201], v[44:47], off offset:1024
	s_nop 0
	s_waitcnt lgkmcnt(2)
	v_cndmask_b32_e64 v35, v21, v23, s[4:5]
	v_cndmask_b32_e64 v34, v20, v22, s[4:5]
	v_cndmask_b32_e64 v33, v23, v21, s[4:5]
	v_cndmask_b32_e64 v32, v22, v20, s[4:5]
	v_lshlrev_b32_e32 v40, 16, v32
	v_and_b32_e32 v41, 0xffff0000, v32
	v_lshlrev_b32_e32 v42, 16, v68
	v_and_b32_e32 v43, 0xffff0000, v68
	v_pk_mul_f32 v[40:41], v[42:43], v[40:41]
	v_cvt_pk_bf16_f32 v44, v40, v41
	v_lshlrev_b32_e32 v40, 16, v33
	v_and_b32_e32 v41, 0xffff0000, v33
	v_lshlrev_b32_e32 v42, 16, v69
	v_and_b32_e32 v43, 0xffff0000, v69
	v_pk_mul_f32 v[40:41], v[42:43], v[40:41]
	v_cvt_pk_bf16_f32 v45, v40, v41
	v_lshlrev_b32_e32 v40, 16, v34
	v_and_b32_e32 v41, 0xffff0000, v34
	v_lshlrev_b32_e32 v42, 16, v70
	v_and_b32_e32 v43, 0xffff0000, v70
	v_pk_mul_f32 v[40:41], v[42:43], v[40:41]
	v_cvt_pk_bf16_f32 v46, v40, v41
	v_lshlrev_b32_e32 v40, 16, v35
	v_and_b32_e32 v41, 0xffff0000, v35
	v_lshlrev_b32_e32 v42, 16, v71
	v_and_b32_e32 v43, 0xffff0000, v71
	v_pk_mul_f32 v[40:41], v[42:43], v[40:41]
	v_cvt_pk_bf16_f32 v47, v40, v41
	v_ashrrev_i32_e32 v201, 31, v138
	v_mov_b32_e32 v200, v138
	v_lshlrev_b64 v[200:201], 11, v[200:201]
	v_lshl_add_u64 v[200:201], s[0:1], 0, v[200:201]
	v_lshl_add_u64 v[200:201], v[200:201], 0, v[98:99]
	global_store_dwordx4 v[200:201], v[44:47], off offset:1024
	s_nop 0
	s_waitcnt lgkmcnt(1)
	v_cndmask_b32_e64 v35, v25, v27, s[4:5]
	v_cndmask_b32_e64 v34, v24, v26, s[4:5]
	v_cndmask_b32_e64 v33, v27, v25, s[4:5]
	v_cndmask_b32_e64 v32, v26, v24, s[4:5]
	v_lshlrev_b32_e32 v40, 16, v32
	v_and_b32_e32 v41, 0xffff0000, v32
	v_lshlrev_b32_e32 v42, 16, v72
	v_and_b32_e32 v43, 0xffff0000, v72
	v_pk_mul_f32 v[40:41], v[42:43], v[40:41]
	v_cvt_pk_bf16_f32 v44, v40, v41
	v_lshlrev_b32_e32 v40, 16, v33
	v_and_b32_e32 v41, 0xffff0000, v33
	v_lshlrev_b32_e32 v42, 16, v73
	v_and_b32_e32 v43, 0xffff0000, v73
	v_pk_mul_f32 v[40:41], v[42:43], v[40:41]
	v_cvt_pk_bf16_f32 v45, v40, v41
	v_lshlrev_b32_e32 v40, 16, v34
	v_and_b32_e32 v41, 0xffff0000, v34
	v_lshlrev_b32_e32 v42, 16, v74
	v_and_b32_e32 v43, 0xffff0000, v74
	v_pk_mul_f32 v[40:41], v[42:43], v[40:41]
	v_cvt_pk_bf16_f32 v46, v40, v41
	v_lshlrev_b32_e32 v40, 16, v35
	v_and_b32_e32 v41, 0xffff0000, v35
	v_lshlrev_b32_e32 v42, 16, v75
	v_and_b32_e32 v43, 0xffff0000, v75
	v_pk_mul_f32 v[40:41], v[42:43], v[40:41]
	v_cvt_pk_bf16_f32 v47, v40, v41
	v_ashrrev_i32_e32 v201, 31, v139
	v_mov_b32_e32 v200, v139
	v_lshlrev_b64 v[200:201], 11, v[200:201]
	v_lshl_add_u64 v[200:201], s[0:1], 0, v[200:201]
	v_lshl_add_u64 v[200:201], v[200:201], 0, v[98:99]
	global_store_dwordx4 v[200:201], v[44:47], off offset:1024
	s_nop 0
	s_waitcnt lgkmcnt(0)
	v_cndmask_b32_e64 v35, v29, v31, s[4:5]
	v_cndmask_b32_e64 v34, v28, v30, s[4:5]
	v_cndmask_b32_e64 v33, v31, v29, s[4:5]
	v_cndmask_b32_e64 v32, v30, v28, s[4:5]
	v_lshlrev_b32_e32 v40, 16, v32
	v_and_b32_e32 v41, 0xffff0000, v32
	v_lshlrev_b32_e32 v42, 16, v76
	v_and_b32_e32 v43, 0xffff0000, v76
	v_pk_mul_f32 v[40:41], v[42:43], v[40:41]
	v_cvt_pk_bf16_f32 v44, v40, v41
	v_lshlrev_b32_e32 v40, 16, v33
	v_and_b32_e32 v41, 0xffff0000, v33
	v_lshlrev_b32_e32 v42, 16, v77
	v_and_b32_e32 v43, 0xffff0000, v77
	v_pk_mul_f32 v[40:41], v[42:43], v[40:41]
	v_cvt_pk_bf16_f32 v45, v40, v41
	v_lshlrev_b32_e32 v40, 16, v34
	v_and_b32_e32 v41, 0xffff0000, v34
	v_lshlrev_b32_e32 v42, 16, v78
	v_and_b32_e32 v43, 0xffff0000, v78
	v_pk_mul_f32 v[40:41], v[42:43], v[40:41]
	v_cvt_pk_bf16_f32 v46, v40, v41
	v_lshlrev_b32_e32 v40, 16, v35
	v_and_b32_e32 v41, 0xffff0000, v35
	v_lshlrev_b32_e32 v42, 16, v79
	v_and_b32_e32 v43, 0xffff0000, v79
	v_pk_mul_f32 v[40:41], v[42:43], v[40:41]
	v_cvt_pk_bf16_f32 v47, v40, v41
	v_ashrrev_i32_e32 v201, 31, v140
	v_mov_b32_e32 v200, v140
	v_lshlrev_b64 v[200:201], 11, v[200:201]
	v_lshl_add_u64 v[200:201], s[0:1], 0, v[200:201]
	v_lshl_add_u64 v[200:201], v[200:201], 0, v[98:99]
	global_store_dwordx4 v[200:201], v[44:47], off offset:1024
	s_nop 0
	s_branch .LBB0_299
.Lfb_entry:
	s_and_b32 s23, s75, 1
	s_lshl_b32 s23, s23, 8
	s_add_i32 s24, s23, s18
	s_mov_b32 s17, 0
	s_lshl_b32 s26, s18, 6
	s_mov_b32 s27, 0
	v_lshl_add_u64 v[96:97], v[106:107], 0, s[26:27]
	global_load_dwordx4 v[0:3], v[96:97], off
	global_load_dwordx4 v[4:7], v[96:97], off offset:1024
	v_add_u32_e32 v185, 0x18000, v194
	v_add_u32_e32 v221, s26, v185
	s_lshl_b32 s26, s23, 2
	v_lshl_add_u64 v[96:97], v[100:101], 0, s[26:27]
	global_load_dwordx4 v[80:83], v[96:97], off
	global_load_dwordx4 v[84:87], v[96:97], off offset:32
	global_load_dwordx4 v[88:91], v[96:97], off offset:64
	global_load_dwordx4 v[92:95], v[96:97], off offset:96
	s_waitcnt vmcnt(4)
	ds_write_b128 v221, v[0:3]
	ds_write_b128 v221, v[4:7] offset:1024
	v_or_b32_e32 v221, s24, v149
	v_lshlrev_b32_e32 v221, 1, v221
	s_mov_b32 s8, 0x8000
	s_lshr_b32 s16, s75, 1
	s_mov_b32 s22, 7
	v_mov_b32_e32 v195, v183
	s_ashr_i32 s9, s8, 31
	s_lshl_b64 s[26:27], s[8:9], 11
	s_add_u32 s26, s42, s26
	s_addc_u32 s27, s43, s27
	v_or_b32_e32 v98, s24, v189
	v_lshlrev_b64 v[96:97], s22, v[98:99]
	v_lshl_add_u64 v[96:97], v[96:97], 0, s[16:17]
	v_lshlrev_b64 v[96:97], 8, v[96:97]
	v_lshl_add_u64 v[96:97], s[26:27], 0, v[96:97]
	v_lshlrev_b32_e32 v98, 1, v196
	v_lshl_add_u64 v[96:97], v[96:97], 0, v[98:99]
	s_or_b32 s8, s8, s16
	v_lshlrev_b32_e32 v137, s22, v193
	v_add_u32_e32 v137, s8, v137
	v_lshlrev_b32_e32 v138, s22, v153
	v_add_u32_e32 v138, s8, v138
	v_lshlrev_b32_e32 v139, s22, v154
	v_add_u32_e32 v139, s8, v139
	v_lshlrev_b32_e32 v140, s22, v155
	v_add_u32_e32 v140, s8, v140
	global_load_dwordx4 v[0:3], v[96:97], off
	global_load_dwordx4 v[4:7], v[96:97], off offset:32
	global_load_dwordx4 v[8:11], v[96:97], off offset:64
	global_load_dwordx4 v[12:15], v[96:97], off offset:96
	global_load_dwordx4 v[16:19], v[96:97], off offset:128
	global_load_dwordx4 v[20:23], v[96:97], off offset:160
	global_load_dwordx4 v[24:27], v[96:97], off offset:192
	global_load_dwordx4 v[28:31], v[96:97], off offset:224
	v_lshlrev_b32_e32 v186, 10, v137
	v_add_u32_e32 v186, v186, v221
	global_load_dwordx4 v[48:51], v186, s[76:77]
	v_lshlrev_b32_e32 v186, 10, v138
	v_add_u32_e32 v186, v186, v221
	global_load_dwordx4 v[52:55], v186, s[76:77]
	v_lshlrev_b32_e32 v186, 10, v139
	v_add_u32_e32 v186, v186, v221
	global_load_dwordx4 v[56:59], v186, s[76:77]
	v_lshlrev_b32_e32 v186, 10, v140
	v_add_u32_e32 v186, v186, v221
	global_load_dwordx4 v[60:63], v186, s[76:77]
	s_waitcnt lgkmcnt(0)
	s_barrier
	s_mov_b32 s8, 0xa000
	s_lshr_b32 s16, s75, 1
	s_mov_b32 s22, 7
	v_mov_b32_e32 v141, v183
	s_ashr_i32 s9, s8, 31
	s_lshl_b64 s[26:27], s[8:9], 11
	s_add_u32 s26, s42, s26
	s_addc_u32 s27, s43, s27
	v_or_b32_e32 v98, s24, v189
	v_lshlrev_b64 v[96:97], s22, v[98:99]
	v_lshl_add_u64 v[96:97], v[96:97], 0, s[16:17]
	v_lshlrev_b64 v[96:97], 8, v[96:97]
	v_lshl_add_u64 v[96:97], s[26:27], 0, v[96:97]
	v_lshlrev_b32_e32 v98, 1, v196
	v_lshl_add_u64 v[96:97], v[96:97], 0, v[98:99]
	s_or_b32 s8, s8, s16
	v_lshlrev_b32_e32 v198, s22, v193
	v_add_u32_e32 v198, s8, v198
	v_lshlrev_b32_e32 v199, s22, v153
	v_add_u32_e32 v199, s8, v199
	v_lshlrev_b32_e32 v200, s22, v154
	v_add_u32_e32 v200, s8, v200
	v_lshlrev_b32_e32 v201, s22, v155
	v_add_u32_e32 v201, s8, v201
	v_lshlrev_b32_e32 v186, 10, v198
	v_add_u32_e32 v186, v186, v221
	global_load_dwordx4 v[64:67], v186, s[76:77]
	v_lshlrev_b32_e32 v186, 10, v199
	v_add_u32_e32 v186, v186, v221
	global_load_dwordx4 v[68:71], v186, s[76:77]
	v_lshlrev_b32_e32 v186, 10, v200
	v_add_u32_e32 v186, v186, v221
	global_load_dwordx4 v[72:75], v186, s[76:77]
	v_lshlrev_b32_e32 v186, 10, v201
	v_add_u32_e32 v186, v186, v221
	global_load_dwordx4 v[76:79], v186, s[76:77]
	ds_read_b128 v[32:35], v185 offset:0
	ds_read_b128 v[36:39], v185 offset:1024
	ds_read_b128 v[40:43], v185 offset:2048
	ds_read_b128 v[44:47], v185 offset:3072
	s_waitcnt vmcnt(15)
	s_waitcnt lgkmcnt(2)
	v_mfma_f32_32x32x16_bf16 v[222:237], v[0:3], v[32:35], 0
	v_mfma_f32_32x32x16_bf16 v[238:253], v[0:3], v[36:39], 0
	ds_read_b128 v[32:35], v185 offset:4096
	ds_read_b128 v[36:39], v185 offset:5120
	global_load_dwordx4 v[0:3], v[96:97], off
	s_waitcnt vmcnt(15)
	s_waitcnt lgkmcnt(2)
	v_mfma_f32_32x32x16_bf16 v[222:237], v[4:7], v[40:43], v[222:237]
	v_mfma_f32_32x32x16_bf16 v[238:253], v[4:7], v[44:47], v[238:253]
	ds_read_b128 v[40:43], v185 offset:6144
	ds_read_b128 v[44:47], v185 offset:7168
	global_load_dwordx4 v[4:7], v[96:97], off offset:32
	s_waitcnt vmcnt(15)
	s_waitcnt lgkmcnt(2)
	v_mfma_f32_32x32x16_bf16 v[222:237], v[8:11], v[32:35], v[222:237]
	v_mfma_f32_32x32x16_bf16 v[238:253], v[8:11], v[36:39], v[238:253]
	ds_read_b128 v[32:35], v185 offset:8192
	ds_read_b128 v[36:39], v185 offset:9216
	global_load_dwordx4 v[8:11], v[96:97], off offset:64
	s_waitcnt vmcnt(15)
	s_waitcnt lgkmcnt(2)
	v_mfma_f32_32x32x16_bf16 v[222:237], v[12:15], v[40:43], v[222:237]
	v_mfma_f32_32x32x16_bf16 v[238:253], v[12:15], v[44:47], v[238:253]
	ds_read_b128 v[40:43], v185 offset:10240
	ds_read_b128 v[44:47], v185 offset:11264
	global_load_dwordx4 v[12:15], v[96:97], off offset:96
	s_waitcnt vmcnt(15)
	s_waitcnt lgkmcnt(2)
	v_mfma_f32_32x32x16_bf16 v[222:237], v[16:19], v[32:35], v[222:237]
	v_mfma_f32_32x32x16_bf16 v[238:253], v[16:19], v[36:39], v[238:253]
	ds_read_b128 v[32:35], v185 offset:12288
	ds_read_b128 v[36:39], v185 offset:13312
	global_load_dwordx4 v[16:19], v[96:97], off offset:128
	s_waitcnt vmcnt(15)
	s_waitcnt lgkmcnt(2)
	v_mfma_f32_32x32x16_bf16 v[222:237], v[20:23], v[40:43], v[222:237]
	v_mfma_f32_32x32x16_bf16 v[238:253], v[20:23], v[44:47], v[238:253]
	ds_read_b128 v[40:43], v185 offset:14336
	ds_read_b128 v[44:47], v185 offset:15360
	global_load_dwordx4 v[20:23], v[96:97], off offset:160
	s_waitcnt vmcnt(15)
	s_waitcnt lgkmcnt(2)
	v_mfma_f32_32x32x16_bf16 v[222:237], v[24:27], v[32:35], v[222:237]
	v_mfma_f32_32x32x16_bf16 v[238:253], v[24:27], v[36:39], v[238:253]
	global_load_dwordx4 v[24:27], v[96:97], off offset:192
	s_waitcnt vmcnt(15)
	s_waitcnt lgkmcnt(0)
	v_mfma_f32_32x32x16_bf16 v[222:237], v[28:31], v[40:43], v[222:237]
	v_mfma_f32_32x32x16_bf16 v[238:253], v[28:31], v[44:47], v[238:253]
	global_load_dwordx4 v[28:31], v[96:97], off offset:224
	s_nop 7
	s_nop 7
	v_fma_f32 v222, v195, v222, v80
	v_fma_f32 v223, v195, v223, v81
	v_fma_f32 v224, v195, v224, v82
	v_fma_f32 v225, v195, v225, v83
	v_fma_f32 v226, v195, v226, v84
	v_fma_f32 v227, v195, v227, v85
	v_fma_f32 v228, v195, v228, v86
	v_fma_f32 v229, v195, v229, v87
	v_fma_f32 v230, v195, v230, v88
	v_fma_f32 v231, v195, v231, v89
	v_fma_f32 v232, v195, v232, v90
	v_fma_f32 v233, v195, v233, v91
	v_fma_f32 v234, v195, v234, v92
	v_fma_f32 v235, v195, v235, v93
	v_fma_f32 v236, v195, v236, v94
	v_fma_f32 v237, v195, v237, v95
	v_fma_f32 v238, v195, v238, v80
	v_fma_f32 v239, v195, v239, v81
	v_fma_f32 v240, v195, v240, v82
	v_fma_f32 v241, v195, v241, v83
	v_fma_f32 v242, v195, v242, v84
	v_fma_f32 v243, v195, v243, v85
	v_fma_f32 v244, v195, v244, v86
	v_fma_f32 v245, v195, v245, v87
	v_fma_f32 v246, v195, v246, v88
	v_fma_f32 v247, v195, v247, v89
	v_fma_f32 v248, v195, v248, v90
	v_fma_f32 v249, v195, v249, v91
	v_fma_f32 v250, v195, v250, v92
	v_fma_f32 v251, v195, v251, v93
	v_fma_f32 v252, v195, v252, v94
	v_fma_f32 v253, v195, v253, v95
	v_cvt_pk_bf16_f32 v222, v222, v223
	v_cvt_pk_bf16_f32 v223, v224, v225
	v_cvt_pk_bf16_f32 v224, v226, v227
	v_cvt_pk_bf16_f32 v225, v228, v229
	v_cvt_pk_bf16_f32 v226, v230, v231
	v_cvt_pk_bf16_f32 v227, v232, v233
	v_cvt_pk_bf16_f32 v228, v234, v235
	v_cvt_pk_bf16_f32 v229, v236, v237
	v_cvt_pk_bf16_f32 v230, v238, v239
	v_cvt_pk_bf16_f32 v231, v240, v241
	v_cvt_pk_bf16_f32 v232, v242, v243
	v_cvt_pk_bf16_f32 v233, v244, v245
	v_cvt_pk_bf16_f32 v234, v246, v247
	v_cvt_pk_bf16_f32 v235, v248, v249
	v_cvt_pk_bf16_f32 v236, v250, v251
	v_cvt_pk_bf16_f32 v237, v252, v253
	ds_write2st64_b64 v163, v[222:223], v[230:231] offset1:4
	ds_write2st64_b64 v164, v[224:225], v[232:233] offset1:4
	ds_write2st64_b64 v165, v[226:227], v[234:235] offset1:4
	ds_write2st64_b64 v166, v[228:229], v[236:237] offset1:4
	ds_read_b128 v[238:241], v167
	ds_read_b128 v[242:245], v168
	ds_read_b128 v[246:249], v169
	ds_read_b128 v[250:253], v170
	s_waitcnt lgkmcnt(3)
	s_waitcnt vmcnt(15)
	v_cndmask_b32_e64 v225, v239, v241, s[4:5]
	v_cndmask_b32_e64 v224, v238, v240, s[4:5]
	v_cndmask_b32_e64 v223, v241, v239, s[4:5]
	v_cndmask_b32_e64 v222, v240, v238, s[4:5]
	v_lshlrev_b32_e32 v226, 16, v222
	v_and_b32_e32 v227, 0xffff0000, v222
	v_lshlrev_b32_e32 v228, 16, v48
	v_and_b32_e32 v229, 0xffff0000, v48
	v_pk_mul_f32 v[226:227], v[228:229], v[226:227]
	v_cvt_pk_bf16_f32 v230, v226, v227
	v_lshlrev_b32_e32 v226, 16, v223
	v_and_b32_e32 v227, 0xffff0000, v223
	v_lshlrev_b32_e32 v228, 16, v49
	v_and_b32_e32 v229, 0xffff0000, v49
	v_pk_mul_f32 v[226:227], v[228:229], v[226:227]
	v_cvt_pk_bf16_f32 v231, v226, v227
	v_lshlrev_b32_e32 v226, 16, v224
	v_and_b32_e32 v227, 0xffff0000, v224
	v_lshlrev_b32_e32 v228, 16, v50
	v_and_b32_e32 v229, 0xffff0000, v50
	v_pk_mul_f32 v[226:227], v[228:229], v[226:227]
	v_cvt_pk_bf16_f32 v232, v226, v227
	v_lshlrev_b32_e32 v226, 16, v225
	v_and_b32_e32 v227, 0xffff0000, v225
	v_lshlrev_b32_e32 v228, 16, v51
	v_and_b32_e32 v229, 0xffff0000, v51
	v_pk_mul_f32 v[226:227], v[228:229], v[226:227]
	v_cvt_pk_bf16_f32 v233, v226, v227
	v_lshlrev_b32_e32 v186, 11, v137
	v_add_u32_e32 v186, v186, v221
	global_store_dwordx4 v186, v[230:233], s[0:1] offset:1024
	s_nop 0
	s_waitcnt lgkmcnt(2)
	s_waitcnt vmcnt(15)
	v_cndmask_b32_e64 v225, v243, v245, s[4:5]
	v_cndmask_b32_e64 v224, v242, v244, s[4:5]
	v_cndmask_b32_e64 v223, v245, v243, s[4:5]
	v_cndmask_b32_e64 v222, v244, v242, s[4:5]
	v_lshlrev_b32_e32 v226, 16, v222
	v_and_b32_e32 v227, 0xffff0000, v222
	v_lshlrev_b32_e32 v228, 16, v52
	v_and_b32_e32 v229, 0xffff0000, v52
	v_pk_mul_f32 v[226:227], v[228:229], v[226:227]
	v_cvt_pk_bf16_f32 v230, v226, v227
	v_lshlrev_b32_e32 v226, 16, v223
	v_and_b32_e32 v227, 0xffff0000, v223
	v_lshlrev_b32_e32 v228, 16, v53
	v_and_b32_e32 v229, 0xffff0000, v53
	v_pk_mul_f32 v[226:227], v[228:229], v[226:227]
	v_cvt_pk_bf16_f32 v231, v226, v227
	v_lshlrev_b32_e32 v226, 16, v224
	v_and_b32_e32 v227, 0xffff0000, v224
	v_lshlrev_b32_e32 v228, 16, v54
	v_and_b32_e32 v229, 0xffff0000, v54
	v_pk_mul_f32 v[226:227], v[228:229], v[226:227]
	v_cvt_pk_bf16_f32 v232, v226, v227
	v_lshlrev_b32_e32 v226, 16, v225
	v_and_b32_e32 v227, 0xffff0000, v225
	v_lshlrev_b32_e32 v228, 16, v55
	v_and_b32_e32 v229, 0xffff0000, v55
	v_pk_mul_f32 v[226:227], v[228:229], v[226:227]
	v_cvt_pk_bf16_f32 v233, v226, v227
	v_lshlrev_b32_e32 v186, 11, v138
	v_add_u32_e32 v186, v186, v221
	global_store_dwordx4 v186, v[230:233], s[0:1] offset:1024
	s_nop 0
	s_waitcnt lgkmcnt(1)
	s_waitcnt vmcnt(15)
	v_cndmask_b32_e64 v225, v247, v249, s[4:5]
	v_cndmask_b32_e64 v224, v246, v248, s[4:5]
	v_cndmask_b32_e64 v223, v249, v247, s[4:5]
	v_cndmask_b32_e64 v222, v248, v246, s[4:5]
	v_lshlrev_b32_e32 v226, 16, v222
	v_and_b32_e32 v227, 0xffff0000, v222
	v_lshlrev_b32_e32 v228, 16, v56
	v_and_b32_e32 v229, 0xffff0000, v56
	v_pk_mul_f32 v[226:227], v[228:229], v[226:227]
	v_cvt_pk_bf16_f32 v230, v226, v227
	v_lshlrev_b32_e32 v226, 16, v223
	v_and_b32_e32 v227, 0xffff0000, v223
	v_lshlrev_b32_e32 v228, 16, v57
	v_and_b32_e32 v229, 0xffff0000, v57
	v_pk_mul_f32 v[226:227], v[228:229], v[226:227]
	v_cvt_pk_bf16_f32 v231, v226, v227
	v_lshlrev_b32_e32 v226, 16, v224
	v_and_b32_e32 v227, 0xffff0000, v224
	v_lshlrev_b32_e32 v228, 16, v58
	v_and_b32_e32 v229, 0xffff0000, v58
	v_pk_mul_f32 v[226:227], v[228:229], v[226:227]
	v_cvt_pk_bf16_f32 v232, v226, v227
	v_lshlrev_b32_e32 v226, 16, v225
	v_and_b32_e32 v227, 0xffff0000, v225
	v_lshlrev_b32_e32 v228, 16, v59
	v_and_b32_e32 v229, 0xffff0000, v59
	v_pk_mul_f32 v[226:227], v[228:229], v[226:227]
	v_cvt_pk_bf16_f32 v233, v226, v227
	v_lshlrev_b32_e32 v186, 11, v139
	v_add_u32_e32 v186, v186, v221
	global_store_dwordx4 v186, v[230:233], s[0:1] offset:1024
	s_nop 0
	s_waitcnt lgkmcnt(0)
	s_waitcnt vmcnt(15)
	v_cndmask_b32_e64 v225, v251, v253, s[4:5]
	v_cndmask_b32_e64 v224, v250, v252, s[4:5]
	v_cndmask_b32_e64 v223, v253, v251, s[4:5]
	v_cndmask_b32_e64 v222, v252, v250, s[4:5]
	v_lshlrev_b32_e32 v226, 16, v222
	v_and_b32_e32 v227, 0xffff0000, v222
	v_lshlrev_b32_e32 v228, 16, v60
	v_and_b32_e32 v229, 0xffff0000, v60
	v_pk_mul_f32 v[226:227], v[228:229], v[226:227]
	v_cvt_pk_bf16_f32 v230, v226, v227
	v_lshlrev_b32_e32 v226, 16, v223
	v_and_b32_e32 v227, 0xffff0000, v223
	v_lshlrev_b32_e32 v228, 16, v61
	v_and_b32_e32 v229, 0xffff0000, v61
	v_pk_mul_f32 v[226:227], v[228:229], v[226:227]
	v_cvt_pk_bf16_f32 v231, v226, v227
	v_lshlrev_b32_e32 v226, 16, v224
	v_and_b32_e32 v227, 0xffff0000, v224
	v_lshlrev_b32_e32 v228, 16, v62
	v_and_b32_e32 v229, 0xffff0000, v62
	v_pk_mul_f32 v[226:227], v[228:229], v[226:227]
	v_cvt_pk_bf16_f32 v232, v226, v227
	v_lshlrev_b32_e32 v226, 16, v225
	v_and_b32_e32 v227, 0xffff0000, v225
	v_lshlrev_b32_e32 v228, 16, v63
	v_and_b32_e32 v229, 0xffff0000, v63
	v_pk_mul_f32 v[226:227], v[228:229], v[226:227]
	v_cvt_pk_bf16_f32 v233, v226, v227
	v_lshlrev_b32_e32 v186, 11, v140
	v_add_u32_e32 v186, v186, v221
	global_store_dwordx4 v186, v[230:233], s[0:1] offset:1024
	s_nop 0
	s_lshr_b32 s8, s75, 7
	s_add_i32 s8, s8, 0
	s_lshl_b32 s8, s8, 12
	s_and_b32 s16, s75, 0x7f
	s_lshr_b32 s16, s16, 1
	s_mov_b32 s22, 6
	v_mov_b32_e32 v195, v184
	s_ashr_i32 s9, s8, 31
	s_lshl_b64 s[26:27], s[8:9], 11
	s_add_u32 s26, s42, s26
	s_addc_u32 s27, s43, s27
	v_or_b32_e32 v98, s24, v189
	v_lshlrev_b64 v[96:97], s22, v[98:99]
	v_lshl_add_u64 v[96:97], v[96:97], 0, s[16:17]
	v_lshlrev_b64 v[96:97], 8, v[96:97]
	v_lshl_add_u64 v[96:97], s[26:27], 0, v[96:97]
	v_lshlrev_b32_e32 v98, 1, v196
	v_lshl_add_u64 v[96:97], v[96:97], 0, v[98:99]
	s_or_b32 s8, s8, s16
	v_lshlrev_b32_e32 v137, s22, v193
	v_add_u32_e32 v137, s8, v137
	v_lshlrev_b32_e32 v138, s22, v153
	v_add_u32_e32 v138, s8, v138
	v_lshlrev_b32_e32 v139, s22, v154
	v_add_u32_e32 v139, s8, v139
	v_lshlrev_b32_e32 v140, s22, v155
	v_add_u32_e32 v140, s8, v140
	v_lshlrev_b32_e32 v186, 10, v137
	v_add_u32_e32 v186, v186, v221
	global_load_dwordx4 v[48:51], v186, s[76:77]
	v_lshlrev_b32_e32 v186, 10, v138
	v_add_u32_e32 v186, v186, v221
	global_load_dwordx4 v[52:55], v186, s[76:77]
	v_lshlrev_b32_e32 v186, 10, v139
	v_add_u32_e32 v186, v186, v221
	global_load_dwordx4 v[56:59], v186, s[76:77]
	v_lshlrev_b32_e32 v186, 10, v140
	v_add_u32_e32 v186, v186, v221
	global_load_dwordx4 v[60:63], v186, s[76:77]
	ds_read_b128 v[32:35], v185 offset:0
	ds_read_b128 v[36:39], v185 offset:1024
	ds_read_b128 v[40:43], v185 offset:2048
	ds_read_b128 v[44:47], v185 offset:3072
	s_waitcnt vmcnt(15)
	s_waitcnt lgkmcnt(2)
	v_mfma_f32_32x32x16_bf16 v[222:237], v[0:3], v[32:35], 0
	v_mfma_f32_32x32x16_bf16 v[238:253], v[0:3], v[36:39], 0
	ds_read_b128 v[32:35], v185 offset:4096
	ds_read_b128 v[36:39], v185 offset:5120
	global_load_dwordx4 v[0:3], v[96:97], off
	s_waitcnt vmcnt(15)
	s_waitcnt lgkmcnt(2)
	v_mfma_f32_32x32x16_bf16 v[222:237], v[4:7], v[40:43], v[222:237]
	v_mfma_f32_32x32x16_bf16 v[238:253], v[4:7], v[44:47], v[238:253]
	ds_read_b128 v[40:43], v185 offset:6144
	ds_read_b128 v[44:47], v185 offset:7168
	global_load_dwordx4 v[4:7], v[96:97], off offset:32
	s_waitcnt vmcnt(15)
	s_waitcnt lgkmcnt(2)
	v_mfma_f32_32x32x16_bf16 v[222:237], v[8:11], v[32:35], v[222:237]
	v_mfma_f32_32x32x16_bf16 v[238:253], v[8:11], v[36:39], v[238:253]
	ds_read_b128 v[32:35], v185 offset:8192
	ds_read_b128 v[36:39], v185 offset:9216
	global_load_dwordx4 v[8:11], v[96:97], off offset:64
	s_waitcnt vmcnt(15)
	s_waitcnt lgkmcnt(2)
	v_mfma_f32_32x32x16_bf16 v[222:237], v[12:15], v[40:43], v[222:237]
	v_mfma_f32_32x32x16_bf16 v[238:253], v[12:15], v[44:47], v[238:253]
	ds_read_b128 v[40:43], v185 offset:10240
	ds_read_b128 v[44:47], v185 offset:11264
	global_load_dwordx4 v[12:15], v[96:97], off offset:96
	s_waitcnt vmcnt(15)
	s_waitcnt lgkmcnt(2)
	v_mfma_f32_32x32x16_bf16 v[222:237], v[16:19], v[32:35], v[222:237]
	v_mfma_f32_32x32x16_bf16 v[238:253], v[16:19], v[36:39], v[238:253]
	ds_read_b128 v[32:35], v185 offset:12288
	ds_read_b128 v[36:39], v185 offset:13312
	global_load_dwordx4 v[16:19], v[96:97], off offset:128
	s_waitcnt vmcnt(15)
	s_waitcnt lgkmcnt(2)
	v_mfma_f32_32x32x16_bf16 v[222:237], v[20:23], v[40:43], v[222:237]
	v_mfma_f32_32x32x16_bf16 v[238:253], v[20:23], v[44:47], v[238:253]
	ds_read_b128 v[40:43], v185 offset:14336
	ds_read_b128 v[44:47], v185 offset:15360
	global_load_dwordx4 v[20:23], v[96:97], off offset:160
	s_waitcnt vmcnt(15)
	s_waitcnt lgkmcnt(2)
	v_mfma_f32_32x32x16_bf16 v[222:237], v[24:27], v[32:35], v[222:237]
	v_mfma_f32_32x32x16_bf16 v[238:253], v[24:27], v[36:39], v[238:253]
	global_load_dwordx4 v[24:27], v[96:97], off offset:192
	s_waitcnt vmcnt(15)
	s_waitcnt lgkmcnt(0)
	v_mfma_f32_32x32x16_bf16 v[222:237], v[28:31], v[40:43], v[222:237]
	v_mfma_f32_32x32x16_bf16 v[238:253], v[28:31], v[44:47], v[238:253]
	global_load_dwordx4 v[28:31], v[96:97], off offset:224
	s_nop 7
	s_nop 7
	v_fma_f32 v222, v141, v222, v80
	v_fma_f32 v223, v141, v223, v81
	v_fma_f32 v224, v141, v224, v82
	v_fma_f32 v225, v141, v225, v83
	v_fma_f32 v226, v141, v226, v84
	v_fma_f32 v227, v141, v227, v85
	v_fma_f32 v228, v141, v228, v86
	v_fma_f32 v229, v141, v229, v87
	v_fma_f32 v230, v141, v230, v88
	v_fma_f32 v231, v141, v231, v89
	v_fma_f32 v232, v141, v232, v90
	v_fma_f32 v233, v141, v233, v91
	v_fma_f32 v234, v141, v234, v92
	v_fma_f32 v235, v141, v235, v93
	v_fma_f32 v236, v141, v236, v94
	v_fma_f32 v237, v141, v237, v95
	v_fma_f32 v238, v141, v238, v80
	v_fma_f32 v239, v141, v239, v81
	v_fma_f32 v240, v141, v240, v82
	v_fma_f32 v241, v141, v241, v83
	v_fma_f32 v242, v141, v242, v84
	v_fma_f32 v243, v141, v243, v85
	v_fma_f32 v244, v141, v244, v86
	v_fma_f32 v245, v141, v245, v87
	v_fma_f32 v246, v141, v246, v88
	v_fma_f32 v247, v141, v247, v89
	v_fma_f32 v248, v141, v248, v90
	v_fma_f32 v249, v141, v249, v91
	v_fma_f32 v250, v141, v250, v92
	v_fma_f32 v251, v141, v251, v93
	v_fma_f32 v252, v141, v252, v94
	v_fma_f32 v253, v141, v253, v95
	v_cvt_pk_bf16_f32 v222, v222, v223
	v_cvt_pk_bf16_f32 v223, v224, v225
	v_cvt_pk_bf16_f32 v224, v226, v227
	v_cvt_pk_bf16_f32 v225, v228, v229
	v_cvt_pk_bf16_f32 v226, v230, v231
	v_cvt_pk_bf16_f32 v227, v232, v233
	v_cvt_pk_bf16_f32 v228, v234, v235
	v_cvt_pk_bf16_f32 v229, v236, v237
	v_cvt_pk_bf16_f32 v230, v238, v239
	v_cvt_pk_bf16_f32 v231, v240, v241
	v_cvt_pk_bf16_f32 v232, v242, v243
	v_cvt_pk_bf16_f32 v233, v244, v245
	v_cvt_pk_bf16_f32 v234, v246, v247
	v_cvt_pk_bf16_f32 v235, v248, v249
	v_cvt_pk_bf16_f32 v236, v250, v251
	v_cvt_pk_bf16_f32 v237, v252, v253
	ds_write2st64_b64 v163, v[222:223], v[230:231] offset1:4
	ds_write2st64_b64 v164, v[224:225], v[232:233] offset1:4
	ds_write2st64_b64 v165, v[226:227], v[234:235] offset1:4
	ds_write2st64_b64 v166, v[228:229], v[236:237] offset1:4
	ds_read_b128 v[238:241], v167
	ds_read_b128 v[242:245], v168
	ds_read_b128 v[246:249], v169
	ds_read_b128 v[250:253], v170
	s_waitcnt lgkmcnt(3)
	v_cndmask_b32_e64 v225, v239, v241, s[4:5]
	v_cndmask_b32_e64 v224, v238, v240, s[4:5]
	v_cndmask_b32_e64 v223, v241, v239, s[4:5]
	v_cndmask_b32_e64 v222, v240, v238, s[4:5]
	v_lshlrev_b32_e32 v226, 16, v222
	v_and_b32_e32 v227, 0xffff0000, v222
	v_lshlrev_b32_e32 v228, 16, v64
	v_and_b32_e32 v229, 0xffff0000, v64
	v_pk_mul_f32 v[226:227], v[228:229], v[226:227]
	v_cvt_pk_bf16_f32 v230, v226, v227
	v_lshlrev_b32_e32 v226, 16, v223
	v_and_b32_e32 v227, 0xffff0000, v223
	v_lshlrev_b32_e32 v228, 16, v65
	v_and_b32_e32 v229, 0xffff0000, v65
	v_pk_mul_f32 v[226:227], v[228:229], v[226:227]
	v_cvt_pk_bf16_f32 v231, v226, v227
	v_lshlrev_b32_e32 v226, 16, v224
	v_and_b32_e32 v227, 0xffff0000, v224
	v_lshlrev_b32_e32 v228, 16, v66
	v_and_b32_e32 v229, 0xffff0000, v66
	v_pk_mul_f32 v[226:227], v[228:229], v[226:227]
	v_cvt_pk_bf16_f32 v232, v226, v227
	v_lshlrev_b32_e32 v226, 16, v225
	v_and_b32_e32 v227, 0xffff0000, v225
	v_lshlrev_b32_e32 v228, 16, v67
	v_and_b32_e32 v229, 0xffff0000, v67
	v_pk_mul_f32 v[226:227], v[228:229], v[226:227]
	v_cvt_pk_bf16_f32 v233, v226, v227
	v_lshlrev_b32_e32 v186, 11, v198
	v_add_u32_e32 v186, v186, v221
	global_store_dwordx4 v186, v[230:233], s[0:1] offset:1024
	s_nop 0
	s_waitcnt lgkmcnt(2)
	v_cndmask_b32_e64 v225, v243, v245, s[4:5]
	v_cndmask_b32_e64 v224, v242, v244, s[4:5]
	v_cndmask_b32_e64 v223, v245, v243, s[4:5]
	v_cndmask_b32_e64 v222, v244, v242, s[4:5]
	v_lshlrev_b32_e32 v226, 16, v222
	v_and_b32_e32 v227, 0xffff0000, v222
	v_lshlrev_b32_e32 v228, 16, v68
	v_and_b32_e32 v229, 0xffff0000, v68
	v_pk_mul_f32 v[226:227], v[228:229], v[226:227]
	v_cvt_pk_bf16_f32 v230, v226, v227
	v_lshlrev_b32_e32 v226, 16, v223
	v_and_b32_e32 v227, 0xffff0000, v223
	v_lshlrev_b32_e32 v228, 16, v69
	v_and_b32_e32 v229, 0xffff0000, v69
	v_pk_mul_f32 v[226:227], v[228:229], v[226:227]
	v_cvt_pk_bf16_f32 v231, v226, v227
	v_lshlrev_b32_e32 v226, 16, v224
	v_and_b32_e32 v227, 0xffff0000, v224
	v_lshlrev_b32_e32 v228, 16, v70
	v_and_b32_e32 v229, 0xffff0000, v70
	v_pk_mul_f32 v[226:227], v[228:229], v[226:227]
	v_cvt_pk_bf16_f32 v232, v226, v227
	v_lshlrev_b32_e32 v226, 16, v225
	v_and_b32_e32 v227, 0xffff0000, v225
	v_lshlrev_b32_e32 v228, 16, v71
	v_and_b32_e32 v229, 0xffff0000, v71
	v_pk_mul_f32 v[226:227], v[228:229], v[226:227]
	v_cvt_pk_bf16_f32 v233, v226, v227
	v_lshlrev_b32_e32 v186, 11, v199
	v_add_u32_e32 v186, v186, v221
	global_store_dwordx4 v186, v[230:233], s[0:1] offset:1024
	s_nop 0
	s_waitcnt lgkmcnt(1)
	v_cndmask_b32_e64 v225, v247, v249, s[4:5]
	v_cndmask_b32_e64 v224, v246, v248, s[4:5]
	v_cndmask_b32_e64 v223, v249, v247, s[4:5]
	v_cndmask_b32_e64 v222, v248, v246, s[4:5]
	v_lshlrev_b32_e32 v226, 16, v222
	v_and_b32_e32 v227, 0xffff0000, v222
	v_lshlrev_b32_e32 v228, 16, v72
	v_and_b32_e32 v229, 0xffff0000, v72
	v_pk_mul_f32 v[226:227], v[228:229], v[226:227]
	v_cvt_pk_bf16_f32 v230, v226, v227
	v_lshlrev_b32_e32 v226, 16, v223
	v_and_b32_e32 v227, 0xffff0000, v223
	v_lshlrev_b32_e32 v228, 16, v73
	v_and_b32_e32 v229, 0xffff0000, v73
	v_pk_mul_f32 v[226:227], v[228:229], v[226:227]
	v_cvt_pk_bf16_f32 v231, v226, v227
	v_lshlrev_b32_e32 v226, 16, v224
	v_and_b32_e32 v227, 0xffff0000, v224
	v_lshlrev_b32_e32 v228, 16, v74
	v_and_b32_e32 v229, 0xffff0000, v74
	v_pk_mul_f32 v[226:227], v[228:229], v[226:227]
	v_cvt_pk_bf16_f32 v232, v226, v227
	v_lshlrev_b32_e32 v226, 16, v225
	v_and_b32_e32 v227, 0xffff0000, v225
	v_lshlrev_b32_e32 v228, 16, v75
	v_and_b32_e32 v229, 0xffff0000, v75
	v_pk_mul_f32 v[226:227], v[228:229], v[226:227]
	v_cvt_pk_bf16_f32 v233, v226, v227
	v_lshlrev_b32_e32 v186, 11, v200
	v_add_u32_e32 v186, v186, v221
	global_store_dwordx4 v186, v[230:233], s[0:1] offset:1024
	s_nop 0
	s_waitcnt lgkmcnt(0)
	v_cndmask_b32_e64 v225, v251, v253, s[4:5]
	v_cndmask_b32_e64 v224, v250, v252, s[4:5]
	v_cndmask_b32_e64 v223, v253, v251, s[4:5]
	v_cndmask_b32_e64 v222, v252, v250, s[4:5]
	v_lshlrev_b32_e32 v226, 16, v222
	v_and_b32_e32 v227, 0xffff0000, v222
	v_lshlrev_b32_e32 v228, 16, v76
	v_and_b32_e32 v229, 0xffff0000, v76
	v_pk_mul_f32 v[226:227], v[228:229], v[226:227]
	v_cvt_pk_bf16_f32 v230, v226, v227
	v_lshlrev_b32_e32 v226, 16, v223
	v_and_b32_e32 v227, 0xffff0000, v223
	v_lshlrev_b32_e32 v228, 16, v77
	v_and_b32_e32 v229, 0xffff0000, v77
	v_pk_mul_f32 v[226:227], v[228:229], v[226:227]
	v_cvt_pk_bf16_f32 v231, v226, v227
	v_lshlrev_b32_e32 v226, 16, v224
	v_and_b32_e32 v227, 0xffff0000, v224
	v_lshlrev_b32_e32 v228, 16, v78
	v_and_b32_e32 v229, 0xffff0000, v78
	v_pk_mul_f32 v[226:227], v[228:229], v[226:227]
	v_cvt_pk_bf16_f32 v232, v226, v227
	v_lshlrev_b32_e32 v226, 16, v225
	v_and_b32_e32 v227, 0xffff0000, v225
	v_lshlrev_b32_e32 v228, 16, v79
	v_and_b32_e32 v229, 0xffff0000, v79
	v_pk_mul_f32 v[226:227], v[228:229], v[226:227]
	v_cvt_pk_bf16_f32 v233, v226, v227
	v_lshlrev_b32_e32 v186, 11, v201
	v_add_u32_e32 v186, v186, v221
	global_store_dwordx4 v186, v[230:233], s[0:1] offset:1024
	s_nop 0
	s_lshr_b32 s8, s75, 7
	s_add_i32 s8, s8, 2
	s_lshl_b32 s8, s8, 12
	s_and_b32 s16, s75, 0x7f
	s_lshr_b32 s16, s16, 1
	s_mov_b32 s22, 6
	v_mov_b32_e32 v141, v184
	s_ashr_i32 s9, s8, 31
	s_lshl_b64 s[26:27], s[8:9], 11
	s_add_u32 s26, s42, s26
	s_addc_u32 s27, s43, s27
	v_or_b32_e32 v98, s24, v189
	v_lshlrev_b64 v[96:97], s22, v[98:99]
	v_lshl_add_u64 v[96:97], v[96:97], 0, s[16:17]
	v_lshlrev_b64 v[96:97], 8, v[96:97]
	v_lshl_add_u64 v[96:97], s[26:27], 0, v[96:97]
	v_lshlrev_b32_e32 v98, 1, v196
	v_lshl_add_u64 v[96:97], v[96:97], 0, v[98:99]
	s_or_b32 s8, s8, s16
	v_lshlrev_b32_e32 v198, s22, v193
	v_add_u32_e32 v198, s8, v198
	v_lshlrev_b32_e32 v199, s22, v153
	v_add_u32_e32 v199, s8, v199
	v_lshlrev_b32_e32 v200, s22, v154
	v_add_u32_e32 v200, s8, v200
	v_lshlrev_b32_e32 v201, s22, v155
	v_add_u32_e32 v201, s8, v201
	v_lshlrev_b32_e32 v186, 10, v198
	v_add_u32_e32 v186, v186, v221
	global_load_dwordx4 v[64:67], v186, s[76:77]
	v_lshlrev_b32_e32 v186, 10, v199
	v_add_u32_e32 v186, v186, v221
	global_load_dwordx4 v[68:71], v186, s[76:77]
	v_lshlrev_b32_e32 v186, 10, v200
	v_add_u32_e32 v186, v186, v221
	global_load_dwordx4 v[72:75], v186, s[76:77]
	v_lshlrev_b32_e32 v186, 10, v201
	v_add_u32_e32 v186, v186, v221
	global_load_dwordx4 v[76:79], v186, s[76:77]
	ds_read_b128 v[32:35], v185 offset:0
	ds_read_b128 v[36:39], v185 offset:1024
	ds_read_b128 v[40:43], v185 offset:2048
	ds_read_b128 v[44:47], v185 offset:3072
	s_waitcnt vmcnt(15)
	s_waitcnt lgkmcnt(2)
	v_mfma_f32_32x32x16_bf16 v[222:237], v[0:3], v[32:35], 0
	v_mfma_f32_32x32x16_bf16 v[238:253], v[0:3], v[36:39], 0
	ds_read_b128 v[32:35], v185 offset:4096
	ds_read_b128 v[36:39], v185 offset:5120
	global_load_dwordx4 v[0:3], v[96:97], off
	s_waitcnt vmcnt(15)
	s_waitcnt lgkmcnt(2)
	v_mfma_f32_32x32x16_bf16 v[222:237], v[4:7], v[40:43], v[222:237]
	v_mfma_f32_32x32x16_bf16 v[238:253], v[4:7], v[44:47], v[238:253]
	ds_read_b128 v[40:43], v185 offset:6144
	ds_read_b128 v[44:47], v185 offset:7168
	global_load_dwordx4 v[4:7], v[96:97], off offset:32
	s_waitcnt vmcnt(15)
	s_waitcnt lgkmcnt(2)
	v_mfma_f32_32x32x16_bf16 v[222:237], v[8:11], v[32:35], v[222:237]
	v_mfma_f32_32x32x16_bf16 v[238:253], v[8:11], v[36:39], v[238:253]
	ds_read_b128 v[32:35], v185 offset:8192
	ds_read_b128 v[36:39], v185 offset:9216
	global_load_dwordx4 v[8:11], v[96:97], off offset:64
	s_waitcnt vmcnt(15)
	s_waitcnt lgkmcnt(2)
	v_mfma_f32_32x32x16_bf16 v[222:237], v[12:15], v[40:43], v[222:237]
	v_mfma_f32_32x32x16_bf16 v[238:253], v[12:15], v[44:47], v[238:253]
	ds_read_b128 v[40:43], v185 offset:10240
	ds_read_b128 v[44:47], v185 offset:11264
	global_load_dwordx4 v[12:15], v[96:97], off offset:96
	s_waitcnt vmcnt(15)
	s_waitcnt lgkmcnt(2)
	v_mfma_f32_32x32x16_bf16 v[222:237], v[16:19], v[32:35], v[222:237]
	v_mfma_f32_32x32x16_bf16 v[238:253], v[16:19], v[36:39], v[238:253]
	ds_read_b128 v[32:35], v185 offset:12288
	ds_read_b128 v[36:39], v185 offset:13312
	global_load_dwordx4 v[16:19], v[96:97], off offset:128
	s_waitcnt vmcnt(15)
	s_waitcnt lgkmcnt(2)
	v_mfma_f32_32x32x16_bf16 v[222:237], v[20:23], v[40:43], v[222:237]
	v_mfma_f32_32x32x16_bf16 v[238:253], v[20:23], v[44:47], v[238:253]
	ds_read_b128 v[40:43], v185 offset:14336
	ds_read_b128 v[44:47], v185 offset:15360
	global_load_dwordx4 v[20:23], v[96:97], off offset:160
	s_waitcnt vmcnt(15)
	s_waitcnt lgkmcnt(2)
	v_mfma_f32_32x32x16_bf16 v[222:237], v[24:27], v[32:35], v[222:237]
	v_mfma_f32_32x32x16_bf16 v[238:253], v[24:27], v[36:39], v[238:253]
	global_load_dwordx4 v[24:27], v[96:97], off offset:192
	s_waitcnt vmcnt(15)
	s_waitcnt lgkmcnt(0)
	v_mfma_f32_32x32x16_bf16 v[222:237], v[28:31], v[40:43], v[222:237]
	v_mfma_f32_32x32x16_bf16 v[238:253], v[28:31], v[44:47], v[238:253]
	global_load_dwordx4 v[28:31], v[96:97], off offset:224
	s_nop 7
	s_nop 7
	v_fma_f32 v222, v195, v222, v80
	v_fma_f32 v223, v195, v223, v81
	v_fma_f32 v224, v195, v224, v82
	v_fma_f32 v225, v195, v225, v83
	v_fma_f32 v226, v195, v226, v84
	v_fma_f32 v227, v195, v227, v85
	v_fma_f32 v228, v195, v228, v86
	v_fma_f32 v229, v195, v229, v87
	v_fma_f32 v230, v195, v230, v88
	v_fma_f32 v231, v195, v231, v89
	v_fma_f32 v232, v195, v232, v90
	v_fma_f32 v233, v195, v233, v91
	v_fma_f32 v234, v195, v234, v92
	v_fma_f32 v235, v195, v235, v93
	v_fma_f32 v236, v195, v236, v94
	v_fma_f32 v237, v195, v237, v95
	v_fma_f32 v238, v195, v238, v80
	v_fma_f32 v239, v195, v239, v81
	v_fma_f32 v240, v195, v240, v82
	v_fma_f32 v241, v195, v241, v83
	v_fma_f32 v242, v195, v242, v84
	v_fma_f32 v243, v195, v243, v85
	v_fma_f32 v244, v195, v244, v86
	v_fma_f32 v245, v195, v245, v87
	v_fma_f32 v246, v195, v246, v88
	v_fma_f32 v247, v195, v247, v89
	v_fma_f32 v248, v195, v248, v90
	v_fma_f32 v249, v195, v249, v91
	v_fma_f32 v250, v195, v250, v92
	v_fma_f32 v251, v195, v251, v93
	v_fma_f32 v252, v195, v252, v94
	v_fma_f32 v253, v195, v253, v95
	v_cvt_pk_bf16_f32 v222, v222, v223
	v_cvt_pk_bf16_f32 v223, v224, v225
	v_cvt_pk_bf16_f32 v224, v226, v227
	v_cvt_pk_bf16_f32 v225, v228, v229
	v_cvt_pk_bf16_f32 v226, v230, v231
	v_cvt_pk_bf16_f32 v227, v232, v233
	v_cvt_pk_bf16_f32 v228, v234, v235
	v_cvt_pk_bf16_f32 v229, v236, v237
	v_cvt_pk_bf16_f32 v230, v238, v239
	v_cvt_pk_bf16_f32 v231, v240, v241
	v_cvt_pk_bf16_f32 v232, v242, v243
	v_cvt_pk_bf16_f32 v233, v244, v245
	v_cvt_pk_bf16_f32 v234, v246, v247
	v_cvt_pk_bf16_f32 v235, v248, v249
	v_cvt_pk_bf16_f32 v236, v250, v251
	v_cvt_pk_bf16_f32 v237, v252, v253
	ds_write2st64_b64 v163, v[222:223], v[230:231] offset1:4
	ds_write2st64_b64 v164, v[224:225], v[232:233] offset1:4
	ds_write2st64_b64 v165, v[226:227], v[234:235] offset1:4
	ds_write2st64_b64 v166, v[228:229], v[236:237] offset1:4
	ds_read_b128 v[238:241], v167
	ds_read_b128 v[242:245], v168
	ds_read_b128 v[246:249], v169
	ds_read_b128 v[250:253], v170
	s_waitcnt lgkmcnt(3)
	v_cndmask_b32_e64 v225, v239, v241, s[4:5]
	v_cndmask_b32_e64 v224, v238, v240, s[4:5]
	v_cndmask_b32_e64 v223, v241, v239, s[4:5]
	v_cndmask_b32_e64 v222, v240, v238, s[4:5]
	v_lshlrev_b32_e32 v226, 16, v222
	v_and_b32_e32 v227, 0xffff0000, v222
	v_lshlrev_b32_e32 v228, 16, v48
	v_and_b32_e32 v229, 0xffff0000, v48
	v_pk_mul_f32 v[226:227], v[228:229], v[226:227]
	v_cvt_pk_bf16_f32 v230, v226, v227
	v_lshlrev_b32_e32 v226, 16, v223
	v_and_b32_e32 v227, 0xffff0000, v223
	v_lshlrev_b32_e32 v228, 16, v49
	v_and_b32_e32 v229, 0xffff0000, v49
	v_pk_mul_f32 v[226:227], v[228:229], v[226:227]
	v_cvt_pk_bf16_f32 v231, v226, v227
	v_lshlrev_b32_e32 v226, 16, v224
	v_and_b32_e32 v227, 0xffff0000, v224
	v_lshlrev_b32_e32 v228, 16, v50
	v_and_b32_e32 v229, 0xffff0000, v50
	v_pk_mul_f32 v[226:227], v[228:229], v[226:227]
	v_cvt_pk_bf16_f32 v232, v226, v227
	v_lshlrev_b32_e32 v226, 16, v225
	v_and_b32_e32 v227, 0xffff0000, v225
	v_lshlrev_b32_e32 v228, 16, v51
	v_and_b32_e32 v229, 0xffff0000, v51
	v_pk_mul_f32 v[226:227], v[228:229], v[226:227]
	v_cvt_pk_bf16_f32 v233, v226, v227
	v_lshlrev_b32_e32 v186, 11, v137
	v_add_u32_e32 v186, v186, v221
	global_store_dwordx4 v186, v[230:233], s[0:1] offset:1024
	s_nop 0
	s_waitcnt lgkmcnt(2)
	v_cndmask_b32_e64 v225, v243, v245, s[4:5]
	v_cndmask_b32_e64 v224, v242, v244, s[4:5]
	v_cndmask_b32_e64 v223, v245, v243, s[4:5]
	v_cndmask_b32_e64 v222, v244, v242, s[4:5]
	v_lshlrev_b32_e32 v226, 16, v222
	v_and_b32_e32 v227, 0xffff0000, v222
	v_lshlrev_b32_e32 v228, 16, v52
	v_and_b32_e32 v229, 0xffff0000, v52
	v_pk_mul_f32 v[226:227], v[228:229], v[226:227]
	v_cvt_pk_bf16_f32 v230, v226, v227
	v_lshlrev_b32_e32 v226, 16, v223
	v_and_b32_e32 v227, 0xffff0000, v223
	v_lshlrev_b32_e32 v228, 16, v53
	v_and_b32_e32 v229, 0xffff0000, v53
	v_pk_mul_f32 v[226:227], v[228:229], v[226:227]
	v_cvt_pk_bf16_f32 v231, v226, v227
	v_lshlrev_b32_e32 v226, 16, v224
	v_and_b32_e32 v227, 0xffff0000, v224
	v_lshlrev_b32_e32 v228, 16, v54
	v_and_b32_e32 v229, 0xffff0000, v54
	v_pk_mul_f32 v[226:227], v[228:229], v[226:227]
	v_cvt_pk_bf16_f32 v232, v226, v227
	v_lshlrev_b32_e32 v226, 16, v225
	v_and_b32_e32 v227, 0xffff0000, v225
	v_lshlrev_b32_e32 v228, 16, v55
	v_and_b32_e32 v229, 0xffff0000, v55
	v_pk_mul_f32 v[226:227], v[228:229], v[226:227]
	v_cvt_pk_bf16_f32 v233, v226, v227
	v_lshlrev_b32_e32 v186, 11, v138
	v_add_u32_e32 v186, v186, v221
	global_store_dwordx4 v186, v[230:233], s[0:1] offset:1024
	s_nop 0
	s_waitcnt lgkmcnt(1)
	v_cndmask_b32_e64 v225, v247, v249, s[4:5]
	v_cndmask_b32_e64 v224, v246, v248, s[4:5]
	v_cndmask_b32_e64 v223, v249, v247, s[4:5]
	v_cndmask_b32_e64 v222, v248, v246, s[4:5]
	v_lshlrev_b32_e32 v226, 16, v222
	v_and_b32_e32 v227, 0xffff0000, v222
	v_lshlrev_b32_e32 v228, 16, v56
	v_and_b32_e32 v229, 0xffff0000, v56
	v_pk_mul_f32 v[226:227], v[228:229], v[226:227]
	v_cvt_pk_bf16_f32 v230, v226, v227
	v_lshlrev_b32_e32 v226, 16, v223
	v_and_b32_e32 v227, 0xffff0000, v223
	v_lshlrev_b32_e32 v228, 16, v57
	v_and_b32_e32 v229, 0xffff0000, v57
	v_pk_mul_f32 v[226:227], v[228:229], v[226:227]
	v_cvt_pk_bf16_f32 v231, v226, v227
	v_lshlrev_b32_e32 v226, 16, v224
	v_and_b32_e32 v227, 0xffff0000, v224
	v_lshlrev_b32_e32 v228, 16, v58
	v_and_b32_e32 v229, 0xffff0000, v58
	v_pk_mul_f32 v[226:227], v[228:229], v[226:227]
	v_cvt_pk_bf16_f32 v232, v226, v227
	v_lshlrev_b32_e32 v226, 16, v225
	v_and_b32_e32 v227, 0xffff0000, v225
	v_lshlrev_b32_e32 v228, 16, v59
	v_and_b32_e32 v229, 0xffff0000, v59
	v_pk_mul_f32 v[226:227], v[228:229], v[226:227]
	v_cvt_pk_bf16_f32 v233, v226, v227
	v_lshlrev_b32_e32 v186, 11, v139
	v_add_u32_e32 v186, v186, v221
	global_store_dwordx4 v186, v[230:233], s[0:1] offset:1024
	s_nop 0
	s_waitcnt lgkmcnt(0)
	v_cndmask_b32_e64 v225, v251, v253, s[4:5]
	v_cndmask_b32_e64 v224, v250, v252, s[4:5]
	v_cndmask_b32_e64 v223, v253, v251, s[4:5]
	v_cndmask_b32_e64 v222, v252, v250, s[4:5]
	v_lshlrev_b32_e32 v226, 16, v222
	v_and_b32_e32 v227, 0xffff0000, v222
	v_lshlrev_b32_e32 v228, 16, v60
	v_and_b32_e32 v229, 0xffff0000, v60
	v_pk_mul_f32 v[226:227], v[228:229], v[226:227]
	v_cvt_pk_bf16_f32 v230, v226, v227
	v_lshlrev_b32_e32 v226, 16, v223
	v_and_b32_e32 v227, 0xffff0000, v223
	v_lshlrev_b32_e32 v228, 16, v61
	v_and_b32_e32 v229, 0xffff0000, v61
	v_pk_mul_f32 v[226:227], v[228:229], v[226:227]
	v_cvt_pk_bf16_f32 v231, v226, v227
	v_lshlrev_b32_e32 v226, 16, v224
	v_and_b32_e32 v227, 0xffff0000, v224
	v_lshlrev_b32_e32 v228, 16, v62
	v_and_b32_e32 v229, 0xffff0000, v62
	v_pk_mul_f32 v[226:227], v[228:229], v[226:227]
	v_cvt_pk_bf16_f32 v232, v226, v227
	v_lshlrev_b32_e32 v226, 16, v225
	v_and_b32_e32 v227, 0xffff0000, v225
	v_lshlrev_b32_e32 v228, 16, v63
	v_and_b32_e32 v229, 0xffff0000, v63
	v_pk_mul_f32 v[226:227], v[228:229], v[226:227]
	v_cvt_pk_bf16_f32 v233, v226, v227
	v_lshlrev_b32_e32 v186, 11, v140
	v_add_u32_e32 v186, v186, v221
	global_store_dwordx4 v186, v[230:233], s[0:1] offset:1024
	s_nop 0
	s_lshr_b32 s8, s75, 7
	s_add_i32 s8, s8, 4
	s_lshl_b32 s8, s8, 12
	s_and_b32 s16, s75, 0x7f
	s_lshr_b32 s16, s16, 1
	s_mov_b32 s22, 6
	v_mov_b32_e32 v195, v184
	s_ashr_i32 s9, s8, 31
	s_lshl_b64 s[26:27], s[8:9], 11
	s_add_u32 s26, s42, s26
	s_addc_u32 s27, s43, s27
	v_or_b32_e32 v98, s24, v189
	v_lshlrev_b64 v[96:97], s22, v[98:99]
	v_lshl_add_u64 v[96:97], v[96:97], 0, s[16:17]
	v_lshlrev_b64 v[96:97], 8, v[96:97]
	v_lshl_add_u64 v[96:97], s[26:27], 0, v[96:97]
	v_lshlrev_b32_e32 v98, 1, v196
	v_lshl_add_u64 v[96:97], v[96:97], 0, v[98:99]
	s_or_b32 s8, s8, s16
	v_lshlrev_b32_e32 v137, s22, v193
	v_add_u32_e32 v137, s8, v137
	v_lshlrev_b32_e32 v138, s22, v153
	v_add_u32_e32 v138, s8, v138
	v_lshlrev_b32_e32 v139, s22, v154
	v_add_u32_e32 v139, s8, v139
	v_lshlrev_b32_e32 v140, s22, v155
	v_add_u32_e32 v140, s8, v140
	v_lshlrev_b32_e32 v186, 10, v137
	v_add_u32_e32 v186, v186, v221
	global_load_dwordx4 v[48:51], v186, s[76:77]
	v_lshlrev_b32_e32 v186, 10, v138
	v_add_u32_e32 v186, v186, v221
	global_load_dwordx4 v[52:55], v186, s[76:77]
	v_lshlrev_b32_e32 v186, 10, v139
	v_add_u32_e32 v186, v186, v221
	global_load_dwordx4 v[56:59], v186, s[76:77]
	v_lshlrev_b32_e32 v186, 10, v140
	v_add_u32_e32 v186, v186, v221
	global_load_dwordx4 v[60:63], v186, s[76:77]
	ds_read_b128 v[32:35], v185 offset:0
	ds_read_b128 v[36:39], v185 offset:1024
	ds_read_b128 v[40:43], v185 offset:2048
	ds_read_b128 v[44:47], v185 offset:3072
	s_waitcnt vmcnt(15)
	s_waitcnt lgkmcnt(2)
	v_mfma_f32_32x32x16_bf16 v[222:237], v[0:3], v[32:35], 0
	v_mfma_f32_32x32x16_bf16 v[238:253], v[0:3], v[36:39], 0
	ds_read_b128 v[32:35], v185 offset:4096
	ds_read_b128 v[36:39], v185 offset:5120
	global_load_dwordx4 v[0:3], v[96:97], off
	s_waitcnt vmcnt(15)
	s_waitcnt lgkmcnt(2)
	v_mfma_f32_32x32x16_bf16 v[222:237], v[4:7], v[40:43], v[222:237]
	v_mfma_f32_32x32x16_bf16 v[238:253], v[4:7], v[44:47], v[238:253]
	ds_read_b128 v[40:43], v185 offset:6144
	ds_read_b128 v[44:47], v185 offset:7168
	global_load_dwordx4 v[4:7], v[96:97], off offset:32
	s_waitcnt vmcnt(15)
	s_waitcnt lgkmcnt(2)
	v_mfma_f32_32x32x16_bf16 v[222:237], v[8:11], v[32:35], v[222:237]
	v_mfma_f32_32x32x16_bf16 v[238:253], v[8:11], v[36:39], v[238:253]
	ds_read_b128 v[32:35], v185 offset:8192
	ds_read_b128 v[36:39], v185 offset:9216
	global_load_dwordx4 v[8:11], v[96:97], off offset:64
	s_waitcnt vmcnt(15)
	s_waitcnt lgkmcnt(2)
	v_mfma_f32_32x32x16_bf16 v[222:237], v[12:15], v[40:43], v[222:237]
	v_mfma_f32_32x32x16_bf16 v[238:253], v[12:15], v[44:47], v[238:253]
	ds_read_b128 v[40:43], v185 offset:10240
	ds_read_b128 v[44:47], v185 offset:11264
	global_load_dwordx4 v[12:15], v[96:97], off offset:96
	s_waitcnt vmcnt(15)
	s_waitcnt lgkmcnt(2)
	v_mfma_f32_32x32x16_bf16 v[222:237], v[16:19], v[32:35], v[222:237]
	v_mfma_f32_32x32x16_bf16 v[238:253], v[16:19], v[36:39], v[238:253]
	ds_read_b128 v[32:35], v185 offset:12288
	ds_read_b128 v[36:39], v185 offset:13312
	global_load_dwordx4 v[16:19], v[96:97], off offset:128
	s_waitcnt vmcnt(15)
	s_waitcnt lgkmcnt(2)
	v_mfma_f32_32x32x16_bf16 v[222:237], v[20:23], v[40:43], v[222:237]
	v_mfma_f32_32x32x16_bf16 v[238:253], v[20:23], v[44:47], v[238:253]
	ds_read_b128 v[40:43], v185 offset:14336
	ds_read_b128 v[44:47], v185 offset:15360
	global_load_dwordx4 v[20:23], v[96:97], off offset:160
	s_waitcnt vmcnt(15)
	s_waitcnt lgkmcnt(2)
	v_mfma_f32_32x32x16_bf16 v[222:237], v[24:27], v[32:35], v[222:237]
	v_mfma_f32_32x32x16_bf16 v[238:253], v[24:27], v[36:39], v[238:253]
	global_load_dwordx4 v[24:27], v[96:97], off offset:192
	s_waitcnt vmcnt(15)
	s_waitcnt lgkmcnt(0)
	v_mfma_f32_32x32x16_bf16 v[222:237], v[28:31], v[40:43], v[222:237]
	v_mfma_f32_32x32x16_bf16 v[238:253], v[28:31], v[44:47], v[238:253]
	global_load_dwordx4 v[28:31], v[96:97], off offset:224
	s_nop 7
	s_nop 7
	v_fma_f32 v222, v141, v222, v80
	v_fma_f32 v223, v141, v223, v81
	v_fma_f32 v224, v141, v224, v82
	v_fma_f32 v225, v141, v225, v83
	v_fma_f32 v226, v141, v226, v84
	v_fma_f32 v227, v141, v227, v85
	v_fma_f32 v228, v141, v228, v86
	v_fma_f32 v229, v141, v229, v87
	v_fma_f32 v230, v141, v230, v88
	v_fma_f32 v231, v141, v231, v89
	v_fma_f32 v232, v141, v232, v90
	v_fma_f32 v233, v141, v233, v91
	v_fma_f32 v234, v141, v234, v92
	v_fma_f32 v235, v141, v235, v93
	v_fma_f32 v236, v141, v236, v94
	v_fma_f32 v237, v141, v237, v95
	v_fma_f32 v238, v141, v238, v80
	v_fma_f32 v239, v141, v239, v81
	v_fma_f32 v240, v141, v240, v82
	v_fma_f32 v241, v141, v241, v83
	v_fma_f32 v242, v141, v242, v84
	v_fma_f32 v243, v141, v243, v85
	v_fma_f32 v244, v141, v244, v86
	v_fma_f32 v245, v141, v245, v87
	v_fma_f32 v246, v141, v246, v88
	v_fma_f32 v247, v141, v247, v89
	v_fma_f32 v248, v141, v248, v90
	v_fma_f32 v249, v141, v249, v91
	v_fma_f32 v250, v141, v250, v92
	v_fma_f32 v251, v141, v251, v93
	v_fma_f32 v252, v141, v252, v94
	v_fma_f32 v253, v141, v253, v95
	v_cvt_pk_bf16_f32 v222, v222, v223
	v_cvt_pk_bf16_f32 v223, v224, v225
	v_cvt_pk_bf16_f32 v224, v226, v227
	v_cvt_pk_bf16_f32 v225, v228, v229
	v_cvt_pk_bf16_f32 v226, v230, v231
	v_cvt_pk_bf16_f32 v227, v232, v233
	v_cvt_pk_bf16_f32 v228, v234, v235
	v_cvt_pk_bf16_f32 v229, v236, v237
	v_cvt_pk_bf16_f32 v230, v238, v239
	v_cvt_pk_bf16_f32 v231, v240, v241
	v_cvt_pk_bf16_f32 v232, v242, v243
	v_cvt_pk_bf16_f32 v233, v244, v245
	v_cvt_pk_bf16_f32 v234, v246, v247
	v_cvt_pk_bf16_f32 v235, v248, v249
	v_cvt_pk_bf16_f32 v236, v250, v251
	v_cvt_pk_bf16_f32 v237, v252, v253
	ds_write2st64_b64 v163, v[222:223], v[230:231] offset1:4
	ds_write2st64_b64 v164, v[224:225], v[232:233] offset1:4
	ds_write2st64_b64 v165, v[226:227], v[234:235] offset1:4
	ds_write2st64_b64 v166, v[228:229], v[236:237] offset1:4
	ds_read_b128 v[238:241], v167
	ds_read_b128 v[242:245], v168
	ds_read_b128 v[246:249], v169
	ds_read_b128 v[250:253], v170
	s_waitcnt lgkmcnt(3)
	v_cndmask_b32_e64 v225, v239, v241, s[4:5]
	v_cndmask_b32_e64 v224, v238, v240, s[4:5]
	v_cndmask_b32_e64 v223, v241, v239, s[4:5]
	v_cndmask_b32_e64 v222, v240, v238, s[4:5]
	v_lshlrev_b32_e32 v226, 16, v222
	v_and_b32_e32 v227, 0xffff0000, v222
	v_lshlrev_b32_e32 v228, 16, v64
	v_and_b32_e32 v229, 0xffff0000, v64
	v_pk_mul_f32 v[226:227], v[228:229], v[226:227]
	v_cvt_pk_bf16_f32 v230, v226, v227
	v_lshlrev_b32_e32 v226, 16, v223
	v_and_b32_e32 v227, 0xffff0000, v223
	v_lshlrev_b32_e32 v228, 16, v65
	v_and_b32_e32 v229, 0xffff0000, v65
	v_pk_mul_f32 v[226:227], v[228:229], v[226:227]
	v_cvt_pk_bf16_f32 v231, v226, v227
	v_lshlrev_b32_e32 v226, 16, v224
	v_and_b32_e32 v227, 0xffff0000, v224
	v_lshlrev_b32_e32 v228, 16, v66
	v_and_b32_e32 v229, 0xffff0000, v66
	v_pk_mul_f32 v[226:227], v[228:229], v[226:227]
	v_cvt_pk_bf16_f32 v232, v226, v227
	v_lshlrev_b32_e32 v226, 16, v225
	v_and_b32_e32 v227, 0xffff0000, v225
	v_lshlrev_b32_e32 v228, 16, v67
	v_and_b32_e32 v229, 0xffff0000, v67
	v_pk_mul_f32 v[226:227], v[228:229], v[226:227]
	v_cvt_pk_bf16_f32 v233, v226, v227
	v_lshlrev_b32_e32 v186, 11, v198
	v_add_u32_e32 v186, v186, v221
	global_store_dwordx4 v186, v[230:233], s[0:1] offset:1024
	s_nop 0
	s_waitcnt lgkmcnt(2)
	v_cndmask_b32_e64 v225, v243, v245, s[4:5]
	v_cndmask_b32_e64 v224, v242, v244, s[4:5]
	v_cndmask_b32_e64 v223, v245, v243, s[4:5]
	v_cndmask_b32_e64 v222, v244, v242, s[4:5]
	v_lshlrev_b32_e32 v226, 16, v222
	v_and_b32_e32 v227, 0xffff0000, v222
	v_lshlrev_b32_e32 v228, 16, v68
	v_and_b32_e32 v229, 0xffff0000, v68
	v_pk_mul_f32 v[226:227], v[228:229], v[226:227]
	v_cvt_pk_bf16_f32 v230, v226, v227
	v_lshlrev_b32_e32 v226, 16, v223
	v_and_b32_e32 v227, 0xffff0000, v223
	v_lshlrev_b32_e32 v228, 16, v69
	v_and_b32_e32 v229, 0xffff0000, v69
	v_pk_mul_f32 v[226:227], v[228:229], v[226:227]
	v_cvt_pk_bf16_f32 v231, v226, v227
	v_lshlrev_b32_e32 v226, 16, v224
	v_and_b32_e32 v227, 0xffff0000, v224
	v_lshlrev_b32_e32 v228, 16, v70
	v_and_b32_e32 v229, 0xffff0000, v70
	v_pk_mul_f32 v[226:227], v[228:229], v[226:227]
	v_cvt_pk_bf16_f32 v232, v226, v227
	v_lshlrev_b32_e32 v226, 16, v225
	v_and_b32_e32 v227, 0xffff0000, v225
	v_lshlrev_b32_e32 v228, 16, v71
	v_and_b32_e32 v229, 0xffff0000, v71
	v_pk_mul_f32 v[226:227], v[228:229], v[226:227]
	v_cvt_pk_bf16_f32 v233, v226, v227
	v_lshlrev_b32_e32 v186, 11, v199
	v_add_u32_e32 v186, v186, v221
	global_store_dwordx4 v186, v[230:233], s[0:1] offset:1024
	s_nop 0
	s_waitcnt lgkmcnt(1)
	v_cndmask_b32_e64 v225, v247, v249, s[4:5]
	v_cndmask_b32_e64 v224, v246, v248, s[4:5]
	v_cndmask_b32_e64 v223, v249, v247, s[4:5]
	v_cndmask_b32_e64 v222, v248, v246, s[4:5]
	v_lshlrev_b32_e32 v226, 16, v222
	v_and_b32_e32 v227, 0xffff0000, v222
	v_lshlrev_b32_e32 v228, 16, v72
	v_and_b32_e32 v229, 0xffff0000, v72
	v_pk_mul_f32 v[226:227], v[228:229], v[226:227]
	v_cvt_pk_bf16_f32 v230, v226, v227
	v_lshlrev_b32_e32 v226, 16, v223
	v_and_b32_e32 v227, 0xffff0000, v223
	v_lshlrev_b32_e32 v228, 16, v73
	v_and_b32_e32 v229, 0xffff0000, v73
	v_pk_mul_f32 v[226:227], v[228:229], v[226:227]
	v_cvt_pk_bf16_f32 v231, v226, v227
	v_lshlrev_b32_e32 v226, 16, v224
	v_and_b32_e32 v227, 0xffff0000, v224
	v_lshlrev_b32_e32 v228, 16, v74
	v_and_b32_e32 v229, 0xffff0000, v74
	v_pk_mul_f32 v[226:227], v[228:229], v[226:227]
	v_cvt_pk_bf16_f32 v232, v226, v227
	v_lshlrev_b32_e32 v226, 16, v225
	v_and_b32_e32 v227, 0xffff0000, v225
	v_lshlrev_b32_e32 v228, 16, v75
	v_and_b32_e32 v229, 0xffff0000, v75
	v_pk_mul_f32 v[226:227], v[228:229], v[226:227]
	v_cvt_pk_bf16_f32 v233, v226, v227
	v_lshlrev_b32_e32 v186, 11, v200
	v_add_u32_e32 v186, v186, v221
	global_store_dwordx4 v186, v[230:233], s[0:1] offset:1024
	s_nop 0
	s_waitcnt lgkmcnt(0)
	v_cndmask_b32_e64 v225, v251, v253, s[4:5]
	v_cndmask_b32_e64 v224, v250, v252, s[4:5]
	v_cndmask_b32_e64 v223, v253, v251, s[4:5]
	v_cndmask_b32_e64 v222, v252, v250, s[4:5]
	v_lshlrev_b32_e32 v226, 16, v222
	v_and_b32_e32 v227, 0xffff0000, v222
	v_lshlrev_b32_e32 v228, 16, v76
	v_and_b32_e32 v229, 0xffff0000, v76
	v_pk_mul_f32 v[226:227], v[228:229], v[226:227]
	v_cvt_pk_bf16_f32 v230, v226, v227
	v_lshlrev_b32_e32 v226, 16, v223
	v_and_b32_e32 v227, 0xffff0000, v223
	v_lshlrev_b32_e32 v228, 16, v77
	v_and_b32_e32 v229, 0xffff0000, v77
	v_pk_mul_f32 v[226:227], v[228:229], v[226:227]
	v_cvt_pk_bf16_f32 v231, v226, v227
	v_lshlrev_b32_e32 v226, 16, v224
	v_and_b32_e32 v227, 0xffff0000, v224
	v_lshlrev_b32_e32 v228, 16, v78
	v_and_b32_e32 v229, 0xffff0000, v78
	v_pk_mul_f32 v[226:227], v[228:229], v[226:227]
	v_cvt_pk_bf16_f32 v232, v226, v227
	v_lshlrev_b32_e32 v226, 16, v225
	v_and_b32_e32 v227, 0xffff0000, v225
	v_lshlrev_b32_e32 v228, 16, v79
	v_and_b32_e32 v229, 0xffff0000, v79
	v_pk_mul_f32 v[226:227], v[228:229], v[226:227]
	v_cvt_pk_bf16_f32 v233, v226, v227
	v_lshlrev_b32_e32 v186, 11, v201
	v_add_u32_e32 v186, v186, v221
	global_store_dwordx4 v186, v[230:233], s[0:1] offset:1024
	s_nop 0
	s_lshr_b32 s8, s75, 7
	s_add_i32 s8, s8, 6
	s_lshl_b32 s8, s8, 12
	s_and_b32 s16, s75, 0x7f
	s_lshr_b32 s16, s16, 1
	s_mov_b32 s22, 6
	v_mov_b32_e32 v141, v184
	s_ashr_i32 s9, s8, 31
	s_lshl_b64 s[26:27], s[8:9], 11
	s_add_u32 s26, s42, s26
	s_addc_u32 s27, s43, s27
	v_or_b32_e32 v98, s24, v189
	v_lshlrev_b64 v[96:97], s22, v[98:99]
	v_lshl_add_u64 v[96:97], v[96:97], 0, s[16:17]
	v_lshlrev_b64 v[96:97], 8, v[96:97]
	v_lshl_add_u64 v[96:97], s[26:27], 0, v[96:97]
	v_lshlrev_b32_e32 v98, 1, v196
	v_lshl_add_u64 v[96:97], v[96:97], 0, v[98:99]
	s_or_b32 s8, s8, s16
	v_lshlrev_b32_e32 v198, s22, v193
	v_add_u32_e32 v198, s8, v198
	v_lshlrev_b32_e32 v199, s22, v153
	v_add_u32_e32 v199, s8, v199
	v_lshlrev_b32_e32 v200, s22, v154
	v_add_u32_e32 v200, s8, v200
	v_lshlrev_b32_e32 v201, s22, v155
	v_add_u32_e32 v201, s8, v201
	v_lshlrev_b32_e32 v186, 10, v198
	v_add_u32_e32 v186, v186, v221
	global_load_dwordx4 v[64:67], v186, s[76:77]
	v_lshlrev_b32_e32 v186, 10, v199
	v_add_u32_e32 v186, v186, v221
	global_load_dwordx4 v[68:71], v186, s[76:77]
	v_lshlrev_b32_e32 v186, 10, v200
	v_add_u32_e32 v186, v186, v221
	global_load_dwordx4 v[72:75], v186, s[76:77]
	v_lshlrev_b32_e32 v186, 10, v201
	v_add_u32_e32 v186, v186, v221
	global_load_dwordx4 v[76:79], v186, s[76:77]
	ds_read_b128 v[32:35], v185 offset:0
	ds_read_b128 v[36:39], v185 offset:1024
	ds_read_b128 v[40:43], v185 offset:2048
	ds_read_b128 v[44:47], v185 offset:3072
	s_waitcnt vmcnt(15)
	s_waitcnt lgkmcnt(2)
	v_mfma_f32_32x32x16_bf16 v[222:237], v[0:3], v[32:35], 0
	v_mfma_f32_32x32x16_bf16 v[238:253], v[0:3], v[36:39], 0
	ds_read_b128 v[32:35], v185 offset:4096
	ds_read_b128 v[36:39], v185 offset:5120
	global_load_dwordx4 v[0:3], v[96:97], off
	s_waitcnt vmcnt(15)
	s_waitcnt lgkmcnt(2)
	v_mfma_f32_32x32x16_bf16 v[222:237], v[4:7], v[40:43], v[222:237]
	v_mfma_f32_32x32x16_bf16 v[238:253], v[4:7], v[44:47], v[238:253]
	ds_read_b128 v[40:43], v185 offset:6144
	ds_read_b128 v[44:47], v185 offset:7168
	global_load_dwordx4 v[4:7], v[96:97], off offset:32
	s_waitcnt vmcnt(15)
	s_waitcnt lgkmcnt(2)
	v_mfma_f32_32x32x16_bf16 v[222:237], v[8:11], v[32:35], v[222:237]
	v_mfma_f32_32x32x16_bf16 v[238:253], v[8:11], v[36:39], v[238:253]
	ds_read_b128 v[32:35], v185 offset:8192
	ds_read_b128 v[36:39], v185 offset:9216
	global_load_dwordx4 v[8:11], v[96:97], off offset:64
	s_waitcnt vmcnt(15)
	s_waitcnt lgkmcnt(2)
	v_mfma_f32_32x32x16_bf16 v[222:237], v[12:15], v[40:43], v[222:237]
	v_mfma_f32_32x32x16_bf16 v[238:253], v[12:15], v[44:47], v[238:253]
	ds_read_b128 v[40:43], v185 offset:10240
	ds_read_b128 v[44:47], v185 offset:11264
	global_load_dwordx4 v[12:15], v[96:97], off offset:96
	s_waitcnt vmcnt(15)
	s_waitcnt lgkmcnt(2)
	v_mfma_f32_32x32x16_bf16 v[222:237], v[16:19], v[32:35], v[222:237]
	v_mfma_f32_32x32x16_bf16 v[238:253], v[16:19], v[36:39], v[238:253]
	ds_read_b128 v[32:35], v185 offset:12288
	ds_read_b128 v[36:39], v185 offset:13312
	global_load_dwordx4 v[16:19], v[96:97], off offset:128
	s_waitcnt vmcnt(15)
	s_waitcnt lgkmcnt(2)
	v_mfma_f32_32x32x16_bf16 v[222:237], v[20:23], v[40:43], v[222:237]
	v_mfma_f32_32x32x16_bf16 v[238:253], v[20:23], v[44:47], v[238:253]
	ds_read_b128 v[40:43], v185 offset:14336
	ds_read_b128 v[44:47], v185 offset:15360
	global_load_dwordx4 v[20:23], v[96:97], off offset:160
	s_waitcnt vmcnt(15)
	s_waitcnt lgkmcnt(2)
	v_mfma_f32_32x32x16_bf16 v[222:237], v[24:27], v[32:35], v[222:237]
	v_mfma_f32_32x32x16_bf16 v[238:253], v[24:27], v[36:39], v[238:253]
	global_load_dwordx4 v[24:27], v[96:97], off offset:192
	s_waitcnt vmcnt(15)
	s_waitcnt lgkmcnt(0)
	v_mfma_f32_32x32x16_bf16 v[222:237], v[28:31], v[40:43], v[222:237]
	v_mfma_f32_32x32x16_bf16 v[238:253], v[28:31], v[44:47], v[238:253]
	global_load_dwordx4 v[28:31], v[96:97], off offset:224
	s_nop 7
	s_nop 7
	v_fma_f32 v222, v195, v222, v80
	v_fma_f32 v223, v195, v223, v81
	v_fma_f32 v224, v195, v224, v82
	v_fma_f32 v225, v195, v225, v83
	v_fma_f32 v226, v195, v226, v84
	v_fma_f32 v227, v195, v227, v85
	v_fma_f32 v228, v195, v228, v86
	v_fma_f32 v229, v195, v229, v87
	v_fma_f32 v230, v195, v230, v88
	v_fma_f32 v231, v195, v231, v89
	v_fma_f32 v232, v195, v232, v90
	v_fma_f32 v233, v195, v233, v91
	v_fma_f32 v234, v195, v234, v92
	v_fma_f32 v235, v195, v235, v93
	v_fma_f32 v236, v195, v236, v94
	v_fma_f32 v237, v195, v237, v95
	v_fma_f32 v238, v195, v238, v80
	v_fma_f32 v239, v195, v239, v81
	v_fma_f32 v240, v195, v240, v82
	v_fma_f32 v241, v195, v241, v83
	v_fma_f32 v242, v195, v242, v84
	v_fma_f32 v243, v195, v243, v85
	v_fma_f32 v244, v195, v244, v86
	v_fma_f32 v245, v195, v245, v87
	v_fma_f32 v246, v195, v246, v88
	v_fma_f32 v247, v195, v247, v89
	v_fma_f32 v248, v195, v248, v90
	v_fma_f32 v249, v195, v249, v91
	v_fma_f32 v250, v195, v250, v92
	v_fma_f32 v251, v195, v251, v93
	v_fma_f32 v252, v195, v252, v94
	v_fma_f32 v253, v195, v253, v95
	v_cvt_pk_bf16_f32 v222, v222, v223
	v_cvt_pk_bf16_f32 v223, v224, v225
	v_cvt_pk_bf16_f32 v224, v226, v227
	v_cvt_pk_bf16_f32 v225, v228, v229
	v_cvt_pk_bf16_f32 v226, v230, v231
	v_cvt_pk_bf16_f32 v227, v232, v233
	v_cvt_pk_bf16_f32 v228, v234, v235
	v_cvt_pk_bf16_f32 v229, v236, v237
	v_cvt_pk_bf16_f32 v230, v238, v239
	v_cvt_pk_bf16_f32 v231, v240, v241
	v_cvt_pk_bf16_f32 v232, v242, v243
	v_cvt_pk_bf16_f32 v233, v244, v245
	v_cvt_pk_bf16_f32 v234, v246, v247
	v_cvt_pk_bf16_f32 v235, v248, v249
	v_cvt_pk_bf16_f32 v236, v250, v251
	v_cvt_pk_bf16_f32 v237, v252, v253
	ds_write2st64_b64 v163, v[222:223], v[230:231] offset1:4
	ds_write2st64_b64 v164, v[224:225], v[232:233] offset1:4
	ds_write2st64_b64 v165, v[226:227], v[234:235] offset1:4
	ds_write2st64_b64 v166, v[228:229], v[236:237] offset1:4
	ds_read_b128 v[238:241], v167
	ds_read_b128 v[242:245], v168
	ds_read_b128 v[246:249], v169
	ds_read_b128 v[250:253], v170
	s_waitcnt lgkmcnt(3)
	v_cndmask_b32_e64 v225, v239, v241, s[4:5]
	v_cndmask_b32_e64 v224, v238, v240, s[4:5]
	v_cndmask_b32_e64 v223, v241, v239, s[4:5]
	v_cndmask_b32_e64 v222, v240, v238, s[4:5]
	v_lshlrev_b32_e32 v226, 16, v222
	v_and_b32_e32 v227, 0xffff0000, v222
	v_lshlrev_b32_e32 v228, 16, v48
	v_and_b32_e32 v229, 0xffff0000, v48
	v_pk_mul_f32 v[226:227], v[228:229], v[226:227]
	v_cvt_pk_bf16_f32 v230, v226, v227
	v_lshlrev_b32_e32 v226, 16, v223
	v_and_b32_e32 v227, 0xffff0000, v223
	v_lshlrev_b32_e32 v228, 16, v49
	v_and_b32_e32 v229, 0xffff0000, v49
	v_pk_mul_f32 v[226:227], v[228:229], v[226:227]
	v_cvt_pk_bf16_f32 v231, v226, v227
	v_lshlrev_b32_e32 v226, 16, v224
	v_and_b32_e32 v227, 0xffff0000, v224
	v_lshlrev_b32_e32 v228, 16, v50
	v_and_b32_e32 v229, 0xffff0000, v50
	v_pk_mul_f32 v[226:227], v[228:229], v[226:227]
	v_cvt_pk_bf16_f32 v232, v226, v227
	v_lshlrev_b32_e32 v226, 16, v225
	v_and_b32_e32 v227, 0xffff0000, v225
	v_lshlrev_b32_e32 v228, 16, v51
	v_and_b32_e32 v229, 0xffff0000, v51
	v_pk_mul_f32 v[226:227], v[228:229], v[226:227]
	v_cvt_pk_bf16_f32 v233, v226, v227
	v_lshlrev_b32_e32 v186, 11, v137
	v_add_u32_e32 v186, v186, v221
	global_store_dwordx4 v186, v[230:233], s[0:1] offset:1024
	s_nop 0
	s_waitcnt lgkmcnt(2)
	v_cndmask_b32_e64 v225, v243, v245, s[4:5]
	v_cndmask_b32_e64 v224, v242, v244, s[4:5]
	v_cndmask_b32_e64 v223, v245, v243, s[4:5]
	v_cndmask_b32_e64 v222, v244, v242, s[4:5]
	v_lshlrev_b32_e32 v226, 16, v222
	v_and_b32_e32 v227, 0xffff0000, v222
	v_lshlrev_b32_e32 v228, 16, v52
	v_and_b32_e32 v229, 0xffff0000, v52
	v_pk_mul_f32 v[226:227], v[228:229], v[226:227]
	v_cvt_pk_bf16_f32 v230, v226, v227
	v_lshlrev_b32_e32 v226, 16, v223
	v_and_b32_e32 v227, 0xffff0000, v223
	v_lshlrev_b32_e32 v228, 16, v53
	v_and_b32_e32 v229, 0xffff0000, v53
	v_pk_mul_f32 v[226:227], v[228:229], v[226:227]
	v_cvt_pk_bf16_f32 v231, v226, v227
	v_lshlrev_b32_e32 v226, 16, v224
	v_and_b32_e32 v227, 0xffff0000, v224
	v_lshlrev_b32_e32 v228, 16, v54
	v_and_b32_e32 v229, 0xffff0000, v54
	v_pk_mul_f32 v[226:227], v[228:229], v[226:227]
	v_cvt_pk_bf16_f32 v232, v226, v227
	v_lshlrev_b32_e32 v226, 16, v225
	v_and_b32_e32 v227, 0xffff0000, v225
	v_lshlrev_b32_e32 v228, 16, v55
	v_and_b32_e32 v229, 0xffff0000, v55
	v_pk_mul_f32 v[226:227], v[228:229], v[226:227]
	v_cvt_pk_bf16_f32 v233, v226, v227
	v_lshlrev_b32_e32 v186, 11, v138
	v_add_u32_e32 v186, v186, v221
	global_store_dwordx4 v186, v[230:233], s[0:1] offset:1024
	s_nop 0
	s_waitcnt lgkmcnt(1)
	v_cndmask_b32_e64 v225, v247, v249, s[4:5]
	v_cndmask_b32_e64 v224, v246, v248, s[4:5]
	v_cndmask_b32_e64 v223, v249, v247, s[4:5]
	v_cndmask_b32_e64 v222, v248, v246, s[4:5]
	v_lshlrev_b32_e32 v226, 16, v222
	v_and_b32_e32 v227, 0xffff0000, v222
	v_lshlrev_b32_e32 v228, 16, v56
	v_and_b32_e32 v229, 0xffff0000, v56
	v_pk_mul_f32 v[226:227], v[228:229], v[226:227]
	v_cvt_pk_bf16_f32 v230, v226, v227
	v_lshlrev_b32_e32 v226, 16, v223
	v_and_b32_e32 v227, 0xffff0000, v223
	v_lshlrev_b32_e32 v228, 16, v57
	v_and_b32_e32 v229, 0xffff0000, v57
	v_pk_mul_f32 v[226:227], v[228:229], v[226:227]
	v_cvt_pk_bf16_f32 v231, v226, v227
	v_lshlrev_b32_e32 v226, 16, v224
	v_and_b32_e32 v227, 0xffff0000, v224
	v_lshlrev_b32_e32 v228, 16, v58
	v_and_b32_e32 v229, 0xffff0000, v58
	v_pk_mul_f32 v[226:227], v[228:229], v[226:227]
	v_cvt_pk_bf16_f32 v232, v226, v227
	v_lshlrev_b32_e32 v226, 16, v225
	v_and_b32_e32 v227, 0xffff0000, v225
	v_lshlrev_b32_e32 v228, 16, v59
	v_and_b32_e32 v229, 0xffff0000, v59
	v_pk_mul_f32 v[226:227], v[228:229], v[226:227]
	v_cvt_pk_bf16_f32 v233, v226, v227
	v_lshlrev_b32_e32 v186, 11, v139
	v_add_u32_e32 v186, v186, v221
	global_store_dwordx4 v186, v[230:233], s[0:1] offset:1024
	s_nop 0
	s_waitcnt lgkmcnt(0)
	v_cndmask_b32_e64 v225, v251, v253, s[4:5]
	v_cndmask_b32_e64 v224, v250, v252, s[4:5]
	v_cndmask_b32_e64 v223, v253, v251, s[4:5]
	v_cndmask_b32_e64 v222, v252, v250, s[4:5]
	v_lshlrev_b32_e32 v226, 16, v222
	v_and_b32_e32 v227, 0xffff0000, v222
	v_lshlrev_b32_e32 v228, 16, v60
	v_and_b32_e32 v229, 0xffff0000, v60
	v_pk_mul_f32 v[226:227], v[228:229], v[226:227]
	v_cvt_pk_bf16_f32 v230, v226, v227
	v_lshlrev_b32_e32 v226, 16, v223
	v_and_b32_e32 v227, 0xffff0000, v223
	v_lshlrev_b32_e32 v228, 16, v61
	v_and_b32_e32 v229, 0xffff0000, v61
	v_pk_mul_f32 v[226:227], v[228:229], v[226:227]
	v_cvt_pk_bf16_f32 v231, v226, v227
	v_lshlrev_b32_e32 v226, 16, v224
	v_and_b32_e32 v227, 0xffff0000, v224
	v_lshlrev_b32_e32 v228, 16, v62
	v_and_b32_e32 v229, 0xffff0000, v62
	v_pk_mul_f32 v[226:227], v[228:229], v[226:227]
	v_cvt_pk_bf16_f32 v232, v226, v227
	v_lshlrev_b32_e32 v226, 16, v225
	v_and_b32_e32 v227, 0xffff0000, v225
	v_lshlrev_b32_e32 v228, 16, v63
	v_and_b32_e32 v229, 0xffff0000, v63
	v_pk_mul_f32 v[226:227], v[228:229], v[226:227]
	v_cvt_pk_bf16_f32 v233, v226, v227
	v_lshlrev_b32_e32 v186, 11, v140
	v_add_u32_e32 v186, v186, v221
	global_store_dwordx4 v186, v[230:233], s[0:1] offset:1024
	s_nop 0
	ds_read_b128 v[32:35], v185 offset:0
	ds_read_b128 v[36:39], v185 offset:1024
	ds_read_b128 v[40:43], v185 offset:2048
	ds_read_b128 v[44:47], v185 offset:3072
	s_waitcnt vmcnt(11)
	s_waitcnt lgkmcnt(2)
	v_mfma_f32_32x32x16_bf16 v[222:237], v[0:3], v[32:35], 0
	v_mfma_f32_32x32x16_bf16 v[238:253], v[0:3], v[36:39], 0
	ds_read_b128 v[32:35], v185 offset:4096
	ds_read_b128 v[36:39], v185 offset:5120
	s_waitcnt vmcnt(10)
	s_waitcnt lgkmcnt(2)
	v_mfma_f32_32x32x16_bf16 v[222:237], v[4:7], v[40:43], v[222:237]
	v_mfma_f32_32x32x16_bf16 v[238:253], v[4:7], v[44:47], v[238:253]
	ds_read_b128 v[40:43], v185 offset:6144
	ds_read_b128 v[44:47], v185 offset:7168
	s_waitcnt vmcnt(9)
	s_waitcnt lgkmcnt(2)
	v_mfma_f32_32x32x16_bf16 v[222:237], v[8:11], v[32:35], v[222:237]
	v_mfma_f32_32x32x16_bf16 v[238:253], v[8:11], v[36:39], v[238:253]
	ds_read_b128 v[32:35], v185 offset:8192
	ds_read_b128 v[36:39], v185 offset:9216
	s_waitcnt vmcnt(8)
	s_waitcnt lgkmcnt(2)
	v_mfma_f32_32x32x16_bf16 v[222:237], v[12:15], v[40:43], v[222:237]
	v_mfma_f32_32x32x16_bf16 v[238:253], v[12:15], v[44:47], v[238:253]
	ds_read_b128 v[40:43], v185 offset:10240
	ds_read_b128 v[44:47], v185 offset:11264
	s_waitcnt vmcnt(7)
	s_waitcnt lgkmcnt(2)
	v_mfma_f32_32x32x16_bf16 v[222:237], v[16:19], v[32:35], v[222:237]
	v_mfma_f32_32x32x16_bf16 v[238:253], v[16:19], v[36:39], v[238:253]
	ds_read_b128 v[32:35], v185 offset:12288
	ds_read_b128 v[36:39], v185 offset:13312
	s_waitcnt vmcnt(6)
	s_waitcnt lgkmcnt(2)
	v_mfma_f32_32x32x16_bf16 v[222:237], v[20:23], v[40:43], v[222:237]
	v_mfma_f32_32x32x16_bf16 v[238:253], v[20:23], v[44:47], v[238:253]
	ds_read_b128 v[40:43], v185 offset:14336
	ds_read_b128 v[44:47], v185 offset:15360
	s_waitcnt vmcnt(5)
	s_waitcnt lgkmcnt(2)
	v_mfma_f32_32x32x16_bf16 v[222:237], v[24:27], v[32:35], v[222:237]
	v_mfma_f32_32x32x16_bf16 v[238:253], v[24:27], v[36:39], v[238:253]
	s_waitcnt vmcnt(4)
	s_waitcnt lgkmcnt(0)
	v_mfma_f32_32x32x16_bf16 v[222:237], v[28:31], v[40:43], v[222:237]
	v_mfma_f32_32x32x16_bf16 v[238:253], v[28:31], v[44:47], v[238:253]
	s_nop 7
	s_nop 7
	v_fma_f32 v222, v141, v222, v80
	v_fma_f32 v223, v141, v223, v81
	v_fma_f32 v224, v141, v224, v82
	v_fma_f32 v225, v141, v225, v83
	v_fma_f32 v226, v141, v226, v84
	v_fma_f32 v227, v141, v227, v85
	v_fma_f32 v228, v141, v228, v86
	v_fma_f32 v229, v141, v229, v87
	v_fma_f32 v230, v141, v230, v88
	v_fma_f32 v231, v141, v231, v89
	v_fma_f32 v232, v141, v232, v90
	v_fma_f32 v233, v141, v233, v91
	v_fma_f32 v234, v141, v234, v92
	v_fma_f32 v235, v141, v235, v93
	v_fma_f32 v236, v141, v236, v94
	v_fma_f32 v237, v141, v237, v95
	v_fma_f32 v238, v141, v238, v80
	v_fma_f32 v239, v141, v239, v81
	v_fma_f32 v240, v141, v240, v82
	v_fma_f32 v241, v141, v241, v83
	v_fma_f32 v242, v141, v242, v84
	v_fma_f32 v243, v141, v243, v85
	v_fma_f32 v244, v141, v244, v86
	v_fma_f32 v245, v141, v245, v87
	v_fma_f32 v246, v141, v246, v88
	v_fma_f32 v247, v141, v247, v89
	v_fma_f32 v248, v141, v248, v90
	v_fma_f32 v249, v141, v249, v91
	v_fma_f32 v250, v141, v250, v92
	v_fma_f32 v251, v141, v251, v93
	v_fma_f32 v252, v141, v252, v94
	v_fma_f32 v253, v141, v253, v95
	v_cvt_pk_bf16_f32 v222, v222, v223
	v_cvt_pk_bf16_f32 v223, v224, v225
	v_cvt_pk_bf16_f32 v224, v226, v227
	v_cvt_pk_bf16_f32 v225, v228, v229
	v_cvt_pk_bf16_f32 v226, v230, v231
	v_cvt_pk_bf16_f32 v227, v232, v233
	v_cvt_pk_bf16_f32 v228, v234, v235
	v_cvt_pk_bf16_f32 v229, v236, v237
	v_cvt_pk_bf16_f32 v230, v238, v239
	v_cvt_pk_bf16_f32 v231, v240, v241
	v_cvt_pk_bf16_f32 v232, v242, v243
	v_cvt_pk_bf16_f32 v233, v244, v245
	v_cvt_pk_bf16_f32 v234, v246, v247
	v_cvt_pk_bf16_f32 v235, v248, v249
	v_cvt_pk_bf16_f32 v236, v250, v251
	v_cvt_pk_bf16_f32 v237, v252, v253
	ds_write2st64_b64 v163, v[222:223], v[230:231] offset1:4
	ds_write2st64_b64 v164, v[224:225], v[232:233] offset1:4
	ds_write2st64_b64 v165, v[226:227], v[234:235] offset1:4
	ds_write2st64_b64 v166, v[228:229], v[236:237] offset1:4
	ds_read_b128 v[238:241], v167
	ds_read_b128 v[242:245], v168
	ds_read_b128 v[246:249], v169
	ds_read_b128 v[250:253], v170
	s_waitcnt lgkmcnt(3)
	v_cndmask_b32_e64 v225, v239, v241, s[4:5]
	v_cndmask_b32_e64 v224, v238, v240, s[4:5]
	v_cndmask_b32_e64 v223, v241, v239, s[4:5]
	v_cndmask_b32_e64 v222, v240, v238, s[4:5]
	v_lshlrev_b32_e32 v226, 16, v222
	v_and_b32_e32 v227, 0xffff0000, v222
	v_lshlrev_b32_e32 v228, 16, v64
	v_and_b32_e32 v229, 0xffff0000, v64
	v_pk_mul_f32 v[226:227], v[228:229], v[226:227]
	v_cvt_pk_bf16_f32 v230, v226, v227
	v_lshlrev_b32_e32 v226, 16, v223
	v_and_b32_e32 v227, 0xffff0000, v223
	v_lshlrev_b32_e32 v228, 16, v65
	v_and_b32_e32 v229, 0xffff0000, v65
	v_pk_mul_f32 v[226:227], v[228:229], v[226:227]
	v_cvt_pk_bf16_f32 v231, v226, v227
	v_lshlrev_b32_e32 v226, 16, v224
	v_and_b32_e32 v227, 0xffff0000, v224
	v_lshlrev_b32_e32 v228, 16, v66
	v_and_b32_e32 v229, 0xffff0000, v66
	v_pk_mul_f32 v[226:227], v[228:229], v[226:227]
	v_cvt_pk_bf16_f32 v232, v226, v227
	v_lshlrev_b32_e32 v226, 16, v225
	v_and_b32_e32 v227, 0xffff0000, v225
	v_lshlrev_b32_e32 v228, 16, v67
	v_and_b32_e32 v229, 0xffff0000, v67
	v_pk_mul_f32 v[226:227], v[228:229], v[226:227]
	v_cvt_pk_bf16_f32 v233, v226, v227
	v_lshlrev_b32_e32 v186, 11, v198
	v_add_u32_e32 v186, v186, v221
	global_store_dwordx4 v186, v[230:233], s[0:1] offset:1024
	s_nop 0
	s_waitcnt lgkmcnt(2)
	v_cndmask_b32_e64 v225, v243, v245, s[4:5]
	v_cndmask_b32_e64 v224, v242, v244, s[4:5]
	v_cndmask_b32_e64 v223, v245, v243, s[4:5]
	v_cndmask_b32_e64 v222, v244, v242, s[4:5]
	v_lshlrev_b32_e32 v226, 16, v222
	v_and_b32_e32 v227, 0xffff0000, v222
	v_lshlrev_b32_e32 v228, 16, v68
	v_and_b32_e32 v229, 0xffff0000, v68
	v_pk_mul_f32 v[226:227], v[228:229], v[226:227]
	v_cvt_pk_bf16_f32 v230, v226, v227
	v_lshlrev_b32_e32 v226, 16, v223
	v_and_b32_e32 v227, 0xffff0000, v223
	v_lshlrev_b32_e32 v228, 16, v69
	v_and_b32_e32 v229, 0xffff0000, v69
	v_pk_mul_f32 v[226:227], v[228:229], v[226:227]
	v_cvt_pk_bf16_f32 v231, v226, v227
	v_lshlrev_b32_e32 v226, 16, v224
	v_and_b32_e32 v227, 0xffff0000, v224
	v_lshlrev_b32_e32 v228, 16, v70
	v_and_b32_e32 v229, 0xffff0000, v70
	v_pk_mul_f32 v[226:227], v[228:229], v[226:227]
	v_cvt_pk_bf16_f32 v232, v226, v227
	v_lshlrev_b32_e32 v226, 16, v225
	v_and_b32_e32 v227, 0xffff0000, v225
	v_lshlrev_b32_e32 v228, 16, v71
	v_and_b32_e32 v229, 0xffff0000, v71
	v_pk_mul_f32 v[226:227], v[228:229], v[226:227]
	v_cvt_pk_bf16_f32 v233, v226, v227
	v_lshlrev_b32_e32 v186, 11, v199
	v_add_u32_e32 v186, v186, v221
	global_store_dwordx4 v186, v[230:233], s[0:1] offset:1024
	s_nop 0
	s_waitcnt lgkmcnt(1)
	v_cndmask_b32_e64 v225, v247, v249, s[4:5]
	v_cndmask_b32_e64 v224, v246, v248, s[4:5]
	v_cndmask_b32_e64 v223, v249, v247, s[4:5]
	v_cndmask_b32_e64 v222, v248, v246, s[4:5]
	v_lshlrev_b32_e32 v226, 16, v222
	v_and_b32_e32 v227, 0xffff0000, v222
	v_lshlrev_b32_e32 v228, 16, v72
	v_and_b32_e32 v229, 0xffff0000, v72
	v_pk_mul_f32 v[226:227], v[228:229], v[226:227]
	v_cvt_pk_bf16_f32 v230, v226, v227
	v_lshlrev_b32_e32 v226, 16, v223
	v_and_b32_e32 v227, 0xffff0000, v223
	v_lshlrev_b32_e32 v228, 16, v73
	v_and_b32_e32 v229, 0xffff0000, v73
	v_pk_mul_f32 v[226:227], v[228:229], v[226:227]
	v_cvt_pk_bf16_f32 v231, v226, v227
	v_lshlrev_b32_e32 v226, 16, v224
	v_and_b32_e32 v227, 0xffff0000, v224
	v_lshlrev_b32_e32 v228, 16, v74
	v_and_b32_e32 v229, 0xffff0000, v74
	v_pk_mul_f32 v[226:227], v[228:229], v[226:227]
	v_cvt_pk_bf16_f32 v232, v226, v227
	v_lshlrev_b32_e32 v226, 16, v225
	v_and_b32_e32 v227, 0xffff0000, v225
	v_lshlrev_b32_e32 v228, 16, v75
	v_and_b32_e32 v229, 0xffff0000, v75
	v_pk_mul_f32 v[226:227], v[228:229], v[226:227]
	v_cvt_pk_bf16_f32 v233, v226, v227
	v_lshlrev_b32_e32 v186, 11, v200
	v_add_u32_e32 v186, v186, v221
	global_store_dwordx4 v186, v[230:233], s[0:1] offset:1024
	s_nop 0
	s_waitcnt lgkmcnt(0)
	v_cndmask_b32_e64 v225, v251, v253, s[4:5]
	v_cndmask_b32_e64 v224, v250, v252, s[4:5]
	v_cndmask_b32_e64 v223, v253, v251, s[4:5]
	v_cndmask_b32_e64 v222, v252, v250, s[4:5]
	v_lshlrev_b32_e32 v226, 16, v222
	v_and_b32_e32 v227, 0xffff0000, v222
	v_lshlrev_b32_e32 v228, 16, v76
	v_and_b32_e32 v229, 0xffff0000, v76
	v_pk_mul_f32 v[226:227], v[228:229], v[226:227]
	v_cvt_pk_bf16_f32 v230, v226, v227
	v_lshlrev_b32_e32 v226, 16, v223
	v_and_b32_e32 v227, 0xffff0000, v223
	v_lshlrev_b32_e32 v228, 16, v77
	v_and_b32_e32 v229, 0xffff0000, v77
	v_pk_mul_f32 v[226:227], v[228:229], v[226:227]
	v_cvt_pk_bf16_f32 v231, v226, v227
	v_lshlrev_b32_e32 v226, 16, v224
	v_and_b32_e32 v227, 0xffff0000, v224
	v_lshlrev_b32_e32 v228, 16, v78
	v_and_b32_e32 v229, 0xffff0000, v78
	v_pk_mul_f32 v[226:227], v[228:229], v[226:227]
	v_cvt_pk_bf16_f32 v232, v226, v227
	v_lshlrev_b32_e32 v226, 16, v225
	v_and_b32_e32 v227, 0xffff0000, v225
	v_lshlrev_b32_e32 v228, 16, v79
	v_and_b32_e32 v229, 0xffff0000, v79
	v_pk_mul_f32 v[226:227], v[228:229], v[226:227]
	v_cvt_pk_bf16_f32 v233, v226, v227
	v_lshlrev_b32_e32 v186, 11, v201
	v_add_u32_e32 v186, v186, v221
	global_store_dwordx4 v186, v[230:233], s[0:1] offset:1024
	s_nop 0
	s_add_i32 s44, s44, 5
	s_branch .LBB0_299
